# v10 + nt (streaming) hint on the f32 weight loads of the weight-conversion loops (read once per launch)
# speedup vs baseline: 1.0017x; 1.0016x over previous
; #define PHASE_TID(F) do { const int t_ = opaque_tid(); (F).tid = t_; (F).lane = t_ & 63; (F).wave = __builtin_amdgcn_readfirstlane(t_ >> 6); unsigned long long z_ = 0; asm volatile("" : "+s"((F).bx), "+s"((F).G), "+s"(z_)); (F).ws = (F).ws0 + z_; } while (0)
; #define AM_LOAD(itv, dst) do { const int l_ = (itv) / I_IN, r_ = (itv) % I_IN, kb_ = r_ / (NPROJ / 32), nb_ = r_ % (NPROJ / 32); \
;         const float* wp_ = args.in[4] + (size_t)l_ * D * NPROJ + (size_t)(64 * kb_ + (F.lane >> 5)) * NPROJ + 32 * nb_ + (F.lane & 31); \
;         _Pragma("unroll") for (int i_ = 0; i_ < 32; ++i_) dst[i_] = wp_[(size_t)(2 * i_) * NPROJ]; } while (0)
; __device__ __forceinline__ void win_absmax_all(Frame& F, const Args& args) {
;     PHASE_TID(F);
;     const int gw = F.bx * NWAVES + F.wave, NGW = F.G * NWAVES;
;     constexpr int I_IN = (D / 64) * (NPROJ / 32);
;     float rg[32];
;     ...
;     if (gw < DEPTH * I_IN) AM_LOAD(gw, rg);
.LBB0_21:
	v_mov_b32_e32 v1, v0
	s_mov_b64 s[8:9], 0
	v_readfirstlane_b32 s2, v1
	s_ashr_i32 s4, s2, 6
	s_mov_b64 s[2:3], 0
	s_lshl_b32 s2, s70, 3
	s_add_i32 s38, s2, s4
	s_cmpk_gt_i32 s38, 0x1bff
	s_cbranch_scc1 .LBB0_31
	s_mul_hi_i32 s3, s38, 0x92492493
	s_add_i32 s3, s3, s38
	s_lshr_b32 s4, s3, 31
	s_ashr_i32 s3, s3, 10
	s_add_i32 s3, s3, s4
	s_mul_i32 s4, s3, 0x700
	s_sub_i32 s4, s38, s4
	s_mul_i32 s5, s4, 0x4925
	s_lshr_b32 s10, s5, 31
	s_ashr_i32 s5, s5, 21
	s_add_i32 s10, s5, s10
	s_mul_i32 s5, s10, 0x70
	v_readlane_b32 s12, v253, 2
	v_bfe_u32 v33, v1, 5, 1
	s_lshl_b32 s2, s56, 3
	s_sub_i32 s4, s4, s5
	s_mul_hi_i32 s5, s3, 0xe00000
	s_mul_i32 s3, s3, 0xe00000
	v_readlane_b32 s20, v253, 10
	v_lshl_or_b32 v2, s10, 6, v33
	s_sext_i32_i16 s11, s4
	v_readlane_b32 s21, v253, 11
	s_add_u32 s4, s20, s3
	v_mul_i32_i24_e32 v2, 0x3800, v2
	s_addc_u32 s5, s21, s5
	v_ashrrev_i32_e32 v3, 31, v2
	v_lshl_add_u64 v[2:3], s[4:5], 0, v[2:3]
	s_lshl_b32 s4, s11, 5
	s_ashr_i32 s5, s4, 31
	v_and_b32_e32 v4, 31, v1
	v_lshl_add_u64 v[2:3], s[4:5], 2, v[2:3]
	v_mov_b32_e32 v35, 0
	v_lshlrev_b32_e32 v34, 2, v4
	v_lshl_add_u64 v[2:3], v[2:3], 0, v[34:35]
	s_movk_i32 s3, 0x7000
	v_readlane_b32 s14, v253, 4
	v_add_co_u32_e32 v6, vcc, s3, v2
	s_mov_b32 s14, 0xe000
	s_nop 0
	v_addc_co_u32_e32 v7, vcc, 0, v3, vcc
	v_readlane_b32 s15, v253, 5
	v_add_co_u32_e32 v8, vcc, s14, v2
	s_mov_b32 s15, 0x15000
	s_nop 0
	v_addc_co_u32_e32 v9, vcc, 0, v3, vcc
	v_readlane_b32 s16, v253, 6
	v_add_co_u32_e32 v10, vcc, s15, v2
	s_mov_b32 s16, 0x1c000
	s_nop 0
	v_addc_co_u32_e32 v11, vcc, 0, v3, vcc
	v_readlane_b32 s17, v253, 7
	v_add_co_u32_e32 v12, vcc, s16, v2
	s_mov_b32 s17, 0x23000
	s_nop 0
	v_addc_co_u32_e32 v13, vcc, 0, v3, vcc
	v_readlane_b32 s18, v253, 8
	v_add_co_u32_e32 v14, vcc, s17, v2
	s_mov_b32 s18, 0x2a000
	s_nop 0
	v_addc_co_u32_e32 v15, vcc, 0, v3, vcc
	v_readlane_b32 s19, v253, 9
	v_add_co_u32_e32 v16, vcc, s18, v2
	s_mov_b32 s19, 0x31000
	s_nop 0
	v_addc_co_u32_e32 v17, vcc, 0, v3, vcc
	v_add_co_u32_e32 v18, vcc, s19, v2
	s_mov_b32 s20, 0x38000
	s_nop 0
	v_addc_co_u32_e32 v19, vcc, 0, v3, vcc
	global_load_dword v36, v[2:3], off nt
	global_load_dword v37, v[6:7], off nt
	global_load_dword v38, v[8:9], off nt
	global_load_dword v39, v[10:11], off nt
	global_load_dword v40, v[12:13], off nt
	global_load_dword v41, v[14:15], off nt
	global_load_dword v42, v[16:17], off nt
	global_load_dword v43, v[18:19], off nt
	v_add_co_u32_e32 v6, vcc, s20, v2
	s_mov_b32 s21, 0x3f000
	s_nop 0
	v_addc_co_u32_e32 v7, vcc, 0, v3, vcc
	v_readlane_b32 s22, v253, 12
	v_add_co_u32_e32 v8, vcc, s21, v2
	s_mov_b32 s22, 0x46000
	s_nop 0
	v_addc_co_u32_e32 v9, vcc, 0, v3, vcc
	v_readlane_b32 s23, v253, 13
	v_add_co_u32_e32 v10, vcc, s22, v2
	s_mov_b32 s23, 0x4d000
	s_nop 0
	v_addc_co_u32_e32 v11, vcc, 0, v3, vcc
	v_readlane_b32 s24, v253, 14
	v_add_co_u32_e32 v12, vcc, s23, v2
	s_mov_b32 s24, 0x54000
	s_nop 0
	v_addc_co_u32_e32 v13, vcc, 0, v3, vcc
	v_readlane_b32 s25, v253, 15
	v_add_co_u32_e32 v14, vcc, s24, v2
	s_mov_b32 s25, 0x5b000
	s_nop 0
	v_addc_co_u32_e32 v15, vcc, 0, v3, vcc
	v_readlane_b32 s26, v253, 16
	v_add_co_u32_e32 v16, vcc, s25, v2
	s_mov_b32 s26, 0x62000
	s_nop 0
	v_addc_co_u32_e32 v17, vcc, 0, v3, vcc
	v_readlane_b32 s27, v253, 17
	v_add_co_u32_e32 v18, vcc, s26, v2
	s_mov_b32 s27, 0x69000
	s_nop 0
	v_addc_co_u32_e32 v19, vcc, 0, v3, vcc
	v_add_co_u32_e32 v20, vcc, s27, v2
	s_mov_b32 s29, 0x70000
	s_nop 0
	v_addc_co_u32_e32 v21, vcc, 0, v3, vcc
	global_load_dword v44, v[6:7], off nt
	global_load_dword v45, v[8:9], off nt
	global_load_dword v46, v[10:11], off nt
	global_load_dword v47, v[12:13], off nt
	global_load_dword v48, v[14:15], off nt
; #define AM_LOAD(itv, dst) do { const int l_ = (itv) / I_IN, r_ = (itv) % I_IN, kb_ = r_ / (NPROJ / 32), nb_ = r_ % (NPROJ / 32); \
;         const float* wp_ = args.in[4] + (size_t)l_ * D * NPROJ + (size_t)(64 * kb_ + (F.lane >> 5)) * NPROJ + 32 * nb_ + (F.lane & 31); \
;         _Pragma("unroll") for (int i_ = 0; i_ < 32; ++i_) dst[i_] = wp_[(size_t)(2 * i_) * NPROJ]; } while (0)
; __device__ __forceinline__ void win_absmax_all(Frame& F, const Args& args) {
;     ...
;     if (gw < DEPTH * I_IN) AM_LOAD(gw, rg);
;     for (int it = gw; it < DEPTH * I_IN; it += NGW) {
;         float nrg[32]; const bool hn = it + NGW < DEPTH * I_IN;
;         if (hn) AM_LOAD(it + NGW, nrg);
;         const int l = it / I_IN, r = it % I_IN, nb = r % (NPROJ / 32);
;         float am = 0.f;
; #pragma unroll
;         for (int i = 0; i < 32; ++i) am = fmaxf(am, fabsf(rg[i]));
;         am = fmaxf(am, __shfl_xor(am, 32));
;         if (F.lane < 32) __hip_atomic_fetch_max((unsigned*)(F.ctl + CW_WMAX + l * NPROJ + 32 * nb + F.lane), __builtin_bit_cast(unsigned, am), RLX_AGENT);
	global_load_dword v49, v[16:17], off nt
	global_load_dword v50, v[18:19], off nt
	global_load_dword v52, v[20:21], off nt
	v_add_co_u32_e32 v6, vcc, s29, v2
	s_mov_b32 s30, 0x77000
	s_nop 0
	v_addc_co_u32_e32 v7, vcc, 0, v3, vcc
	v_add_co_u32_e32 v8, vcc, s30, v2
	s_mov_b32 s31, 0x7e000
	s_nop 0
	v_addc_co_u32_e32 v9, vcc, 0, v3, vcc
	v_add_co_u32_e32 v10, vcc, s31, v2
	s_mov_b32 s33, 0x85000
	s_nop 0
	v_addc_co_u32_e32 v11, vcc, 0, v3, vcc
	v_add_co_u32_e32 v12, vcc, s33, v2
	s_mov_b32 s34, 0x8c000
	s_nop 0
	v_addc_co_u32_e32 v13, vcc, 0, v3, vcc
	v_add_co_u32_e32 v14, vcc, s34, v2
	s_mov_b32 s35, 0x93000
	s_nop 0
	v_addc_co_u32_e32 v15, vcc, 0, v3, vcc
	v_add_co_u32_e32 v16, vcc, s35, v2
	s_mov_b32 s36, 0x9a000
	s_nop 0
	v_addc_co_u32_e32 v17, vcc, 0, v3, vcc
	v_add_co_u32_e32 v18, vcc, s36, v2
	s_mov_b32 s37, 0xa1000
	s_nop 0
	v_addc_co_u32_e32 v19, vcc, 0, v3, vcc
	v_add_co_u32_e32 v20, vcc, s37, v2
	s_mov_b32 s39, 0xa8000
	s_nop 0
	v_addc_co_u32_e32 v21, vcc, 0, v3, vcc
	global_load_dword v54, v[6:7], off nt
	global_load_dword v55, v[8:9], off nt
	global_load_dword v56, v[10:11], off nt
	global_load_dword v57, v[12:13], off nt
	global_load_dword v58, v[14:15], off nt
	global_load_dword v59, v[16:17], off nt
	global_load_dword v60, v[18:19], off nt
	global_load_dword v61, v[20:21], off nt
	v_add_co_u32_e32 v6, vcc, s39, v2
	s_mov_b32 s40, 0xaf000
	s_nop 0
	v_addc_co_u32_e32 v7, vcc, 0, v3, vcc
	v_add_co_u32_e32 v8, vcc, s40, v2
	s_mov_b32 s41, 0xb6000
	s_nop 0
	v_addc_co_u32_e32 v9, vcc, 0, v3, vcc
	v_add_co_u32_e32 v10, vcc, s41, v2
	s_mov_b32 s42, 0xbd000
	s_nop 0
	v_addc_co_u32_e32 v11, vcc, 0, v3, vcc
	v_add_co_u32_e32 v12, vcc, s42, v2
	s_mov_b32 s43, 0xc4000
	s_nop 0
	v_addc_co_u32_e32 v13, vcc, 0, v3, vcc
	v_add_co_u32_e32 v14, vcc, s43, v2
	s_mov_b32 s4, 0xcb000
	s_nop 0
	v_addc_co_u32_e32 v15, vcc, 0, v3, vcc
	v_add_co_u32_e32 v16, vcc, s4, v2
	s_mov_b32 s4, 0xd2000
	s_nop 0
	v_addc_co_u32_e32 v17, vcc, 0, v3, vcc
	v_add_co_u32_e32 v18, vcc, s4, v2
	s_mov_b32 s4, 0xd9000
	s_nop 0
	v_addc_co_u32_e32 v19, vcc, 0, v3, vcc
	v_add_co_u32_e32 v2, vcc, s4, v2
	s_add_u32 s44, s48, 0x80000
	s_nop 0
	v_addc_co_u32_e32 v3, vcc, 0, v3, vcc
	global_load_dword v62, v[6:7], off nt
	global_load_dword v63, v[8:9], off nt
	global_load_dword v64, v[10:11], off nt
	global_load_dword v65, v[12:13], off nt
	global_load_dword v66, v[14:15], off nt
	global_load_dword v67, v[16:17], off nt
	global_load_dword v68, v[18:19], off nt
	global_load_dword v69, v[2:3], off nt
	v_and_b32_e32 v6, 63, v1
	v_mbcnt_lo_u32_b32 v1, -1, 0
	v_mbcnt_hi_u32_b32 v1, -1, v1
	v_and_b32_e32 v3, 64, v1
	v_xor_b32_e32 v2, 32, v1
	v_add_u32_e32 v3, 64, v3
	v_cmp_lt_i32_e32 vcc, v2, v3
	v_cmp_gt_u32_e64 s[4:5], 32, v6
	s_addc_u32 s45, s49, 0
	v_cndmask_b32_e32 v1, v1, v2, vcc
	v_lshlrev_b32_e32 v51, 2, v1
	v_mov_b32_e32 v2, v35
	v_mov_b32_e32 v1, v35
	v_lshlrev_b32_e32 v34, 2, v4
	v_lshlrev_b32_e32 v53, 2, v6
	v_mov_b32_e32 v4, v35
	v_mov_b32_e32 v3, v35
	v_mov_b32_e32 v6, v35
	v_mov_b32_e32 v5, v35
	v_mov_b32_e32 v8, v35
	v_mov_b32_e32 v7, v35
	v_mov_b32_e32 v10, v35
	v_mov_b32_e32 v9, v35
	v_mov_b32_e32 v12, v35
	v_mov_b32_e32 v11, v35
	v_mov_b32_e32 v14, v35
	v_mov_b32_e32 v13, v35
	v_mov_b32_e32 v16, v35
	v_mov_b32_e32 v15, v35
	v_mov_b32_e32 v18, v35
	v_mov_b32_e32 v17, v35
	v_mov_b32_e32 v20, v35
	v_mov_b32_e32 v19, v35
	v_mov_b32_e32 v22, v35
	v_mov_b32_e32 v21, v35
	v_mov_b32_e32 v24, v35
	v_mov_b32_e32 v23, v35
	v_mov_b32_e32 v26, v35
	v_mov_b32_e32 v25, v35
	v_mov_b32_e32 v28, v35
	v_mov_b32_e32 v27, v35
	v_mov_b32_e32 v30, v35
	v_mov_b32_e32 v29, v35
	v_mov_b32_e32 v32, v35
	v_mov_b32_e32 v31, v35
	v_readlane_b32 s13, v253, 3
	s_branch .LBB0_24

; #define AM_LOAD(itv, dst) do { const int l_ = (itv) / I_IN, r_ = (itv) % I_IN, kb_ = r_ / (NPROJ / 32), nb_ = r_ % (NPROJ / 32); \
;         const float* wp_ = args.in[4] + (size_t)l_ * D * NPROJ + (size_t)(64 * kb_ + (F.lane >> 5)) * NPROJ + 32 * nb_ + (F.lane & 31); \
;         _Pragma("unroll") for (int i_ = 0; i_ < 32; ++i_) dst[i_] = wp_[(size_t)(2 * i_) * NPROJ]; } while (0)
; __device__ __forceinline__ void win_absmax_all(Frame& F, const Args& args) {
;     ...
;     if (gw < DEPTH * I_IN) AM_LOAD(gw, rg);
;     for (int it = gw; it < DEPTH * I_IN; it += NGW) {
;         float nrg[32]; const bool hn = it + NGW < DEPTH * I_IN;
;         if (hn) AM_LOAD(it + NGW, nrg);
.LBB0_24:
	s_add_i32 s46, s38, s2
	s_cmpk_lt_i32 s46, 0x1c00
	s_cselect_b64 s[10:11], -1, 0
	s_cmpk_gt_i32 s46, 0x1bff
	s_cbranch_scc1 .LBB0_26
	s_mul_hi_i32 s12, s46, 0x92492493
	s_add_i32 s12, s12, s46
	s_lshr_b32 s13, s12, 31
	s_ashr_i32 s12, s12, 10
	s_add_i32 s12, s12, s13
	s_mul_i32 s13, s12, 0xfffff900
	s_add_i32 s13, s46, s13
	s_mul_i32 s47, s13, 0x4925
	s_lshr_b32 s48, s47, 31
	s_ashr_i32 s47, s47, 21
	s_add_i32 s47, s47, s48
	s_mul_i32 s48, s47, 0x70
	s_sub_i32 s13, s13, s48
	s_mov_b32 s50, s70
	v_readlane_b32 s68, v253, 2
	s_sext_i32_i16 s48, s13
	s_mul_hi_i32 s13, s12, 0xe00000
	s_mul_i32 s12, s12, 0xe00000
	v_readlane_b32 s76, v253, 10
	v_lshl_or_b32 v1, s47, 6, v33
	v_readlane_b32 s77, v253, 11
	s_add_u32 s12, s76, s12
	v_mul_i32_i24_e32 v2, 0x3800, v1
	s_addc_u32 s13, s77, s13
	v_ashrrev_i32_e32 v3, 31, v2
	v_lshl_add_u64 v[2:3], s[12:13], 0, v[2:3]
	s_lshl_b32 s12, s48, 5
	s_ashr_i32 s13, s12, 31
	v_lshl_add_u64 v[2:3], s[12:13], 2, v[2:3]
	v_lshl_add_u64 v[2:3], v[2:3], 0, v[34:35]
	v_add_co_u32_e32 v4, vcc, s3, v2
	v_readlane_b32 s70, v253, 4
	s_nop 0
	v_addc_co_u32_e32 v5, vcc, 0, v3, vcc
	v_add_co_u32_e32 v6, vcc, s14, v2
	s_mov_b32 s70, s50
	s_nop 0
	v_addc_co_u32_e32 v7, vcc, 0, v3, vcc
	v_add_co_u32_e32 v8, vcc, s15, v2
	v_readlane_b32 s69, v253, 3
	s_nop 0
	v_addc_co_u32_e32 v9, vcc, 0, v3, vcc
	v_add_co_u32_e32 v10, vcc, s16, v2
	v_readlane_b32 s71, v253, 5
	s_nop 0
	v_addc_co_u32_e32 v11, vcc, 0, v3, vcc
	v_add_co_u32_e32 v12, vcc, s17, v2
	v_readlane_b32 s72, v253, 6
	s_nop 0
	v_addc_co_u32_e32 v13, vcc, 0, v3, vcc
	v_add_co_u32_e32 v14, vcc, s18, v2
	v_readlane_b32 s73, v253, 7
	s_nop 0
	v_addc_co_u32_e32 v15, vcc, 0, v3, vcc
	v_add_co_u32_e32 v16, vcc, s19, v2
	v_readlane_b32 s74, v253, 8
	s_nop 0
	v_addc_co_u32_e32 v17, vcc, 0, v3, vcc
	v_add_co_u32_e32 v18, vcc, s20, v2
	v_readlane_b32 s75, v253, 9
	s_nop 0
	v_addc_co_u32_e32 v19, vcc, 0, v3, vcc
	v_add_co_u32_e32 v20, vcc, s21, v2
	v_readlane_b32 s78, v253, 12
	s_nop 0
	v_addc_co_u32_e32 v21, vcc, 0, v3, vcc
	v_add_co_u32_e32 v22, vcc, s22, v2
	v_readlane_b32 s79, v253, 13
	s_nop 0
	v_addc_co_u32_e32 v23, vcc, 0, v3, vcc
	v_add_co_u32_e32 v24, vcc, s23, v2
	v_readlane_b32 s80, v253, 14
	s_nop 0
	v_addc_co_u32_e32 v25, vcc, 0, v3, vcc
	v_add_co_u32_e32 v26, vcc, s24, v2
	v_readlane_b32 s81, v253, 15
	s_nop 0
	v_addc_co_u32_e32 v27, vcc, 0, v3, vcc
	v_add_co_u32_e32 v28, vcc, s25, v2
	v_readlane_b32 s82, v253, 16
	s_nop 0
	v_addc_co_u32_e32 v29, vcc, 0, v3, vcc
	v_add_co_u32_e32 v30, vcc, s26, v2
	v_readlane_b32 s83, v253, 17
	s_nop 0
	v_addc_co_u32_e32 v31, vcc, 0, v3, vcc
	v_add_co_u32_e32 v70, vcc, s27, v2
	s_nop 1
	v_addc_co_u32_e32 v71, vcc, 0, v3, vcc
	v_add_co_u32_e32 v72, vcc, s29, v2
	s_nop 1
	v_addc_co_u32_e32 v73, vcc, 0, v3, vcc
	v_add_co_u32_e32 v74, vcc, s30, v2
	s_nop 1
	v_addc_co_u32_e32 v75, vcc, 0, v3, vcc
	v_add_co_u32_e32 v76, vcc, s31, v2
	s_nop 1
	v_addc_co_u32_e32 v77, vcc, 0, v3, vcc
	v_add_co_u32_e32 v78, vcc, s33, v2
	s_nop 1
	v_addc_co_u32_e32 v79, vcc, 0, v3, vcc
	v_add_co_u32_e32 v80, vcc, s34, v2
	s_nop 1
	v_addc_co_u32_e32 v81, vcc, 0, v3, vcc
	v_add_co_u32_e32 v82, vcc, s35, v2
	s_nop 1
	v_addc_co_u32_e32 v83, vcc, 0, v3, vcc
	v_add_co_u32_e32 v84, vcc, s36, v2
	s_nop 1
	v_addc_co_u32_e32 v85, vcc, 0, v3, vcc
	v_add_co_u32_e32 v86, vcc, s37, v2
	s_nop 1
	v_addc_co_u32_e32 v87, vcc, 0, v3, vcc
	v_add_co_u32_e32 v88, vcc, s39, v2
	s_nop 1
	v_addc_co_u32_e32 v89, vcc, 0, v3, vcc
	v_add_co_u32_e32 v90, vcc, s40, v2
	s_nop 1
	v_addc_co_u32_e32 v91, vcc, 0, v3, vcc
	v_add_co_u32_e32 v92, vcc, s41, v2
	s_nop 1
	v_addc_co_u32_e32 v93, vcc, 0, v3, vcc
	v_add_co_u32_e32 v94, vcc, s42, v2
	s_nop 1
	v_addc_co_u32_e32 v95, vcc, 0, v3, vcc
	v_add_co_u32_e32 v96, vcc, s43, v2
	s_nop 1
	v_addc_co_u32_e32 v97, vcc, 0, v3, vcc
	v_add_co_u32_e32 v98, vcc, 0xcb000, v2
	s_nop 1
	v_addc_co_u32_e32 v99, vcc, 0, v3, vcc
	v_add_co_u32_e32 v100, vcc, 0xd2000, v2
	s_nop 1
	v_addc_co_u32_e32 v101, vcc, 0, v3, vcc
	v_add_co_u32_e32 v102, vcc, 0xd9000, v2
	s_nop 1
	v_addc_co_u32_e32 v103, vcc, 0, v3, vcc
	global_load_dword v2, v[2:3], off nt
	s_nop 0
	global_load_dword v1, v[4:5], off nt
	s_nop 0
	global_load_dword v4, v[6:7], off nt
	global_load_dword v3, v[8:9], off nt
	s_nop 0
	global_load_dword v6, v[10:11], off nt
	global_load_dword v5, v[12:13], off nt
	global_load_dword v8, v[14:15], off nt
	global_load_dword v7, v[16:17], off nt
	s_nop 0
	global_load_dword v10, v[18:19], off nt
	global_load_dword v9, v[20:21], off nt
	global_load_dword v12, v[22:23], off nt
	global_load_dword v11, v[24:25], off nt
	global_load_dword v14, v[26:27], off nt
	global_load_dword v13, v[28:29], off nt
	global_load_dword v16, v[30:31], off nt
	global_load_dword v15, v[70:71], off nt
	global_load_dword v18, v[72:73], off nt
	global_load_dword v17, v[74:75], off nt
	global_load_dword v20, v[76:77], off nt
	global_load_dword v19, v[78:79], off nt
	global_load_dword v22, v[80:81], off nt
	global_load_dword v21, v[82:83], off nt
	global_load_dword v24, v[84:85], off nt
	global_load_dword v23, v[86:87], off nt
	global_load_dword v26, v[88:89], off nt
	global_load_dword v25, v[90:91], off nt
	global_load_dword v28, v[92:93], off nt
	global_load_dword v27, v[94:95], off nt
	global_load_dword v30, v[96:97], off nt
	global_load_dword v29, v[98:99], off nt
	global_load_dword v32, v[100:101], off nt
	global_load_dword v31, v[102:103], off nt

; #define CONV_LOAD(ci, rg) do { const int nblk_ = (ci).N / 32, kb_ = (ci).item / nblk_, nb_ = (ci).item % nblk_; const float* wp_ = (ci).W + (size_t)(64 * kb_ + (F.lane >> 5)) * (ci).N + 32 * nb_ + (F.lane & 31); \
;         _Pragma("unroll") for (int i_ = 0; i_ < 32; ++i_) rg[i_] = wp_[(size_t)(2 * i_) * (ci).N]; } while (0)
; __device__ __forceinline__ void conv_layer(Frame& F, const Args& args, int layer) {
;     ...
;     ConvItem cur; float rg[32];
;     if (gw < NIT) { cur = decode(gw); CONV_LOAD(cur, rg); }
.LBB0_42:
	s_lshr_b32 s19, s37, 5
	v_cvt_f32_ubyte0_e32 v1, s19
	v_rcp_iflag_f32_e32 v2, v1
	s_sub_i32 s22, 0, s19
	s_lshl_b32 s12, s21, 14
	s_abs_i32 s21, s26
	v_mul_f32_e32 v2, 0x4f7ffffe, v2
	v_cvt_u32_f32_e32 v2, v2
	s_add_i32 s18, s12, 0
	s_lshl_b32 s24, s56, 3
	s_ashr_i32 s12, s26, 31
	v_readfirstlane_b32 s23, v2
	s_mul_i32 s22, s22, s23
	s_mul_hi_u32 s22, s23, s22
	s_add_i32 s23, s23, s22
	s_mul_hi_u32 s22, s21, s23
	s_mul_i32 s23, s22, s19
	s_sub_i32 s21, s21, s23
	s_add_i32 s23, s22, 1
	s_sub_i32 s25, s21, s19
	s_cmp_ge_u32 s21, s19
	s_cselect_b32 s22, s23, s22
	s_cselect_b32 s21, s25, s21
	s_add_i32 s23, s22, 1
	s_cmp_ge_u32 s21, s19
	s_cselect_b32 s21, s23, s22
	s_xor_b32 s21, s21, s12
	v_bfe_u32 v1, v10, 5, 1
	s_sub_i32 s12, s21, s12
	v_lshl_or_b32 v2, s12, 6, v1
	s_mul_i32 s12, s12, s19
	v_mad_i64_i32 v[2:3], s[22:23], v2, s37, 0
	s_sub_i32 s12, s26, s12
	v_lshl_add_u64 v[2:3], v[2:3], 2, s[16:17]
	s_lshl_b32 s16, s12, 5
	s_ashr_i32 s17, s16, 31
	v_and_b32_e32 v22, 31, v10
	v_lshl_add_u64 v[2:3], s[16:17], 2, v[2:3]
	v_mov_b32_e32 v7, 0
	v_lshlrev_b32_e32 v6, 2, v22
	v_lshl_add_u64 v[8:9], v[2:3], 0, v[6:7]
	s_lshl_b32 s12, s37, 3
	v_lshl_add_u64 v[2:3], v[8:9], 0, s[12:13]
	s_lshl_b32 s12, s37, 4
	v_lshl_add_u64 v[4:5], v[8:9], 0, s[12:13]
	s_mul_i32 s12, s37, 24
	v_lshl_add_u64 v[14:15], v[8:9], 0, s[12:13]
	s_lshl_b32 s12, s37, 5
	v_lshl_add_u64 v[16:17], v[8:9], 0, s[12:13]
	s_mul_i32 s12, s37, 40
	v_lshl_add_u64 v[18:19], v[8:9], 0, s[12:13]
	s_mul_i32 s12, s37, 48
	v_lshl_add_u64 v[20:21], v[8:9], 0, s[12:13]
	s_mul_i32 s12, s37, 56
	v_lshl_add_u64 v[26:27], v[8:9], 0, s[12:13]
	s_lshl_b32 s12, s37, 6
	global_load_dword v12, v[8:9], off nt
	global_load_dword v13, v[2:3], off nt
	global_load_dword v24, v[4:5], off nt
	global_load_dword v25, v[14:15], off nt
	s_nop 0
	global_load_dword v2, v[16:17], off nt
	global_load_dword v3, v[18:19], off nt
	global_load_dword v4, v[20:21], off nt
	global_load_dword v5, v[26:27], off nt
	v_lshl_add_u64 v[14:15], v[8:9], 0, s[12:13]
	s_mul_i32 s12, s37, 0x48
	v_lshl_add_u64 v[16:17], v[8:9], 0, s[12:13]
	s_mul_i32 s12, s37, 0x50
	v_lshl_add_u64 v[18:19], v[8:9], 0, s[12:13]
	s_mul_i32 s12, s37, 0x58
	v_lshl_add_u64 v[20:21], v[8:9], 0, s[12:13]
	s_mul_i32 s12, s37, 0x60
	v_lshl_add_u64 v[30:31], v[8:9], 0, s[12:13]
	s_mul_i32 s12, s37, 0x68
	v_lshl_add_u64 v[32:33], v[8:9], 0, s[12:13]
	s_mul_i32 s12, s37, 0x70
	v_lshl_add_u64 v[34:35], v[8:9], 0, s[12:13]
	s_mul_i32 s12, s37, 0x78
	s_waitcnt lgkmcnt(0)
	v_lshl_add_u64 v[36:37], v[8:9], 0, s[12:13]
	s_lshl_b32 s12, s37, 7
	global_load_dword v26, v[14:15], off nt
	global_load_dword v27, v[16:17], off nt
	global_load_dword v28, v[18:19], off nt
	global_load_dword v29, v[20:21], off nt
	s_nop 0
	global_load_dword v30, v[30:31], off nt
	s_nop 0
	global_load_dword v31, v[32:33], off nt
	s_nop 0
	global_load_dword v32, v[34:35], off nt
	global_load_dword v33, v[36:37], off nt
	v_lshl_add_u64 v[14:15], v[8:9], 0, s[12:13]
	s_mul_i32 s12, s37, 0x88
	v_lshl_add_u64 v[16:17], v[8:9], 0, s[12:13]
	s_mul_i32 s12, s37, 0x90
	v_lshl_add_u64 v[18:19], v[8:9], 0, s[12:13]
	s_mul_i32 s12, s37, 0x98
	v_lshl_add_u64 v[20:21], v[8:9], 0, s[12:13]
	s_mul_i32 s12, s37, 0xa0
	v_lshl_add_u64 v[34:35], v[8:9], 0, s[12:13]
	s_mul_i32 s12, s37, 0xa8
	v_lshl_add_u64 v[36:37], v[8:9], 0, s[12:13]
	s_mul_i32 s12, s37, 0xb0
	v_lshl_add_u64 v[38:39], v[8:9], 0, s[12:13]
	s_mul_i32 s12, s37, 0xb8
	v_lshl_add_u64 v[40:41], v[8:9], 0, s[12:13]
	s_mul_i32 s12, s37, 0xc0
	global_load_dword v42, v[14:15], off nt
	global_load_dword v43, v[16:17], off nt
	global_load_dword v44, v[18:19], off nt
	global_load_dword v45, v[20:21], off nt
	global_load_dword v46, v[34:35], off nt
	global_load_dword v47, v[36:37], off nt
	global_load_dword v48, v[38:39], off nt
	global_load_dword v49, v[40:41], off nt
	v_lshl_add_u64 v[14:15], v[8:9], 0, s[12:13]
	s_mul_i32 s12, s37, 0xc8
	v_lshl_add_u64 v[16:17], v[8:9], 0, s[12:13]
	s_mul_i32 s12, s37, 0xd0
	v_lshl_add_u64 v[18:19], v[8:9], 0, s[12:13]
	s_mul_i32 s12, s37, 0xd8
	v_lshl_add_u64 v[20:21], v[8:9], 0, s[12:13]
	s_mul_i32 s12, s37, 0xe0
	v_lshl_add_u64 v[34:35], v[8:9], 0, s[12:13]
	s_mul_i32 s12, s37, 0xe8
	v_lshl_add_u64 v[36:37], v[8:9], 0, s[12:13]
	s_mul_i32 s12, s37, 0xf0
	v_lshl_add_u64 v[38:39], v[8:9], 0, s[12:13]
	s_mul_i32 s12, s37, 0xf8
	v_lshl_add_u64 v[8:9], v[8:9], 0, s[12:13]
	global_load_dword v58, v[14:15], off nt
	global_load_dword v59, v[16:17], off nt
	global_load_dword v60, v[18:19], off nt
	global_load_dword v61, v[20:21], off nt
	global_load_dword v62, v[34:35], off nt
	global_load_dword v63, v[36:37], off nt
	global_load_dword v64, v[38:39], off nt
	global_load_dword v65, v[8:9], off nt
	v_add_u32_e32 v23, s18, v6
	v_lshlrev_b32_e32 v6, 4, v10
	v_and_b32_e32 v8, 48, v6
	v_mul_u32_u24_e32 v6, 0x84, v8
	v_and_b32_e32 v11, 60, v10
	v_add3_u32 v15, s18, v6, v11
	v_lshlrev_b32_e32 v6, 3, v10
	v_bfe_u32 v14, v10, 2, 4
	v_bfe_u32 v17, v10, 3, 3
	v_and_b32_e32 v10, 56, v6
	v_mul_u32_u24_e32 v34, 0x84, v1
	v_mul_u32_u24_e32 v6, 0x84, v10
	v_lshlrev_b32_e32 v11, 2, v17
	v_mov_b32_e32 v9, v7
	v_or_b32_e32 v16, 16, v14
	v_add3_u32 v18, s18, v6, v11
	v_or_b32_e32 v19, 8, v17
	v_or_b32_e32 v20, 16, v17
	v_or_b32_e32 v21, 24, v17
	s_add_i32 s25, s2, s24
	v_mov_b32_e32 v11, s20
	v_lshlrev_b32_e32 v6, 2, v22
	v_add_u32_e32 v22, v23, v34
	s_mov_b32 s27, 0xc3e00000
	v_lshlrev_b32_e32 v10, 1, v10
	v_mov_b32_e32 v23, 0x43e00000
	s_branch .LBB0_44

; #define CONV_LOAD(ci, rg) do { const int nblk_ = (ci).N / 32, kb_ = (ci).item / nblk_, nb_ = (ci).item % nblk_; const float* wp_ = (ci).W + (size_t)(64 * kb_ + (F.lane >> 5)) * (ci).N + 32 * nb_ + (F.lane & 31); \
;         _Pragma("unroll") for (int i_ = 0; i_ < 32; ++i_) rg[i_] = wp_[(size_t)(2 * i_) * (ci).N]; } while (0)
; __device__ __forceinline__ void conv_layer(Frame& F, const Args& args, int layer) {
;     ...
;     for (int it = gw; it < NIT; it += NGW) {
;         ConvItem nxt; float nrg[32]; const bool hn = it + NGW < NIT;
;         if (hn) { nxt = decode(it + NGW); CONV_LOAD(nxt, nrg); }
.LBB0_55:
	s_lshr_b32 s12, s38, 5
	v_cvt_f32_ubyte0_e32 v34, s12
	v_rcp_iflag_f32_e32 v34, v34
	s_sub_i32 s41, 0, s12
	s_abs_i32 s23, s31
	s_ashr_i32 s22, s31, 31
	v_mul_f32_e32 v34, 0x4f7ffffe, v34
	v_cvt_u32_f32_e32 v34, v34
	s_nop 0
	v_readfirstlane_b32 s42, v34
	s_mul_i32 s41, s41, s42
	s_mul_hi_u32 s41, s42, s41
	s_add_i32 s42, s42, s41
	s_mul_hi_u32 s41, s23, s42
	s_mul_i32 s42, s41, s12
	s_sub_i32 s23, s23, s42
	s_add_i32 s43, s41, 1
	s_sub_i32 s42, s23, s12
	s_cmp_ge_u32 s23, s12
	s_cselect_b32 s41, s43, s41
	s_cselect_b32 s23, s42, s23
	s_add_i32 s42, s41, 1
	s_cmp_ge_u32 s23, s12
	s_cselect_b32 s23, s42, s41
	s_xor_b32 s23, s23, s22
	s_sub_i32 s22, s23, s22
	s_mul_i32 s12, s22, s12
	v_lshl_or_b32 v34, s22, 6, v1
	s_sub_i32 s12, s31, s12
	v_mad_i64_i32 v[34:35], s[22:23], v34, s38, 0
	v_lshl_add_u64 v[34:35], v[34:35], 2, s[20:21]
	s_lshl_b32 s20, s12, 5
	s_ashr_i32 s21, s20, 31
	v_lshl_add_u64 v[34:35], s[20:21], 2, v[34:35]
	v_lshl_add_u64 v[74:75], v[34:35], 0, v[6:7]
	s_lshl_b32 s12, s38, 3
	v_lshl_add_u64 v[34:35], v[74:75], 0, s[12:13]
	s_lshl_b32 s12, s38, 4
	v_lshl_add_u64 v[36:37], v[74:75], 0, s[12:13]
	s_mul_i32 s12, s38, 24
	v_lshl_add_u64 v[50:51], v[74:75], 0, s[12:13]
	s_lshl_b32 s12, s38, 5
	v_lshl_add_u64 v[52:53], v[74:75], 0, s[12:13]
	s_mul_i32 s12, s38, 40
	v_lshl_add_u64 v[54:55], v[74:75], 0, s[12:13]
	s_mul_i32 s12, s38, 48
	v_lshl_add_u64 v[56:57], v[74:75], 0, s[12:13]
	s_mul_i32 s12, s38, 56
	v_lshl_add_u64 v[66:67], v[74:75], 0, s[12:13]
	s_lshl_b32 s12, s38, 6
	global_load_dword v41, v[74:75], off nt
	global_load_dword v40, v[34:35], off nt
	global_load_dword v39, v[36:37], off nt
	global_load_dword v38, v[50:51], off nt
	s_nop 0
	global_load_dword v37, v[52:53], off nt
	global_load_dword v36, v[54:55], off nt
	global_load_dword v35, v[56:57], off nt
	global_load_dword v34, v[66:67], off nt
	v_lshl_add_u64 v[50:51], v[74:75], 0, s[12:13]
	s_mul_i32 s12, s38, 0x48
	v_lshl_add_u64 v[52:53], v[74:75], 0, s[12:13]
	s_mul_i32 s12, s38, 0x50
	v_lshl_add_u64 v[54:55], v[74:75], 0, s[12:13]
	s_mul_i32 s12, s38, 0x58
	v_lshl_add_u64 v[66:67], v[74:75], 0, s[12:13]
	s_mul_i32 s12, s38, 0x60
	v_lshl_add_u64 v[68:69], v[74:75], 0, s[12:13]
	s_mul_i32 s12, s38, 0x68
	v_lshl_add_u64 v[70:71], v[74:75], 0, s[12:13]
	s_mul_i32 s12, s38, 0x70
	v_lshl_add_u64 v[72:73], v[74:75], 0, s[12:13]
	s_mul_i32 s12, s38, 0x78
	v_lshl_add_u64 v[76:77], v[74:75], 0, s[12:13]
	s_lshl_b32 s12, s38, 7
	global_load_dword v57, v[50:51], off nt
	global_load_dword v56, v[52:53], off nt
	s_nop 0
	global_load_dword v55, v[54:55], off nt
	s_nop 0
	global_load_dword v54, v[66:67], off nt
	global_load_dword v53, v[68:69], off nt
	global_load_dword v52, v[70:71], off nt
	global_load_dword v51, v[72:73], off nt
	global_load_dword v50, v[76:77], off nt
	v_lshl_add_u64 v[66:67], v[74:75], 0, s[12:13]
	s_mul_i32 s12, s38, 0x88
	v_lshl_add_u64 v[68:69], v[74:75], 0, s[12:13]
	s_mul_i32 s12, s38, 0x90
	v_lshl_add_u64 v[70:71], v[74:75], 0, s[12:13]
	s_mul_i32 s12, s38, 0x98
	v_lshl_add_u64 v[76:77], v[74:75], 0, s[12:13]
	s_mul_i32 s12, s38, 0xa0
	v_lshl_add_u64 v[78:79], v[74:75], 0, s[12:13]
	s_mul_i32 s12, s38, 0xa8
	v_lshl_add_u64 v[80:81], v[74:75], 0, s[12:13]
	s_mul_i32 s12, s38, 0xb0
	v_lshl_add_u64 v[82:83], v[74:75], 0, s[12:13]
	s_mul_i32 s12, s38, 0xb8
	v_lshl_add_u64 v[84:85], v[74:75], 0, s[12:13]
	s_mul_i32 s12, s38, 0xc0
	global_load_dword v73, v[66:67], off nt
	global_load_dword v72, v[68:69], off nt
	s_nop 0
	global_load_dword v71, v[70:71], off nt
	s_nop 0
	global_load_dword v70, v[76:77], off nt
	global_load_dword v69, v[78:79], off nt
	global_load_dword v68, v[80:81], off nt
	global_load_dword v67, v[82:83], off nt
	global_load_dword v66, v[84:85], off nt
	v_lshl_add_u64 v[76:77], v[74:75], 0, s[12:13]
	s_mul_i32 s12, s38, 0xc8
	v_lshl_add_u64 v[78:79], v[74:75], 0, s[12:13]
	s_mul_i32 s12, s38, 0xd0
	v_lshl_add_u64 v[82:83], v[74:75], 0, s[12:13]
	s_mul_i32 s12, s38, 0xd8
	v_lshl_add_u64 v[84:85], v[74:75], 0, s[12:13]
	s_mul_i32 s12, s38, 0xe0
	v_lshl_add_u64 v[86:87], v[74:75], 0, s[12:13]
	s_mul_i32 s12, s38, 0xe8
	v_lshl_add_u64 v[88:89], v[74:75], 0, s[12:13]
	s_mul_i32 s12, s38, 0xf0
	v_lshl_add_u64 v[90:91], v[74:75], 0, s[12:13]
	s_mul_i32 s12, s38, 0xf8
	v_lshl_add_u64 v[92:93], v[74:75], 0, s[12:13]
	global_load_dword v81, v[76:77], off nt
	global_load_dword v80, v[78:79], off nt
	s_nop 0
	global_load_dword v79, v[82:83], off nt
	global_load_dword v78, v[84:85], off nt
	global_load_dword v77, v[86:87], off nt
	global_load_dword v76, v[88:89], off nt
	global_load_dword v75, v[90:91], off nt
	global_load_dword v74, v[92:93], off nt
	v_mov_b32_e32 v82, s40

; #define LAS __attribute__((address_space(3)))
; #define LDS_WAIT() asm volatile("s_waitcnt lgkmcnt(0)" ::: "memory")
; __device__ __forceinline__ void quant8_item(const float* W, int K, int N, signed char* WT, const gu32* wmax, LAS float* scr, int item, int lane) {
;     const int nblk = N / 32, kb = item / nblk, nb = item % nblk, k0 = 64 * kb, n0 = 32 * nb;
; #pragma unroll
;     for (int i = 0; i < 32; ++i) { const int kk = 2 * i + (lane >> 5); scr[kk * 33 + (lane & 31)] = W[(size_t)(k0 + kk) * N + n0 + (lane & 31)]; }
;     LDS_WAIT(); asm volatile("" ::: "memory");
; __device__ __forceinline__ void conv_win(Frame& F, const Args& args, int layer) {
;     ...
;     constexpr int I_IN = (D / 64) * (NPROJ / 32);
;     for (int it = gw; it < I_IN; it += NGW) quant8_item(args.in[4] + (size_t)layer * D * NPROJ, D, NPROJ, (signed char*)(F.ws + WS_WIN), F.ctl + CW_WMAX + layer * NPROJ, scr, it, F.lane);
.LBB0_132:
	s_mul_hi_i32 s4, s2, 0x92492493
	s_add_i32 s4, s4, s2
	s_lshr_b32 s5, s4, 31
	s_ashr_i32 s4, s4, 6
	s_add_i32 s4, s4, s5
	s_lshl_b32 s8, s4, 6
	s_mulk_i32 s4, 0xf200
	s_add_i32 s4, s10, s4
	s_ashr_i32 s5, s4, 31
	v_add_u32_e32 v10, s4, v43
	s_lshl_b64 s[4:5], s[4:5], 2
	v_or_b32_e32 v60, s8, v1
	v_or_b32_e32 v62, s8, v12
	v_or_b32_e32 v64, s8, v13
	v_or_b32_e32 v66, s8, v14
	v_or_b32_e32 v68, s8, v15
	v_or_b32_e32 v70, s8, v16
	v_or_b32_e32 v72, s8, v17
	v_or_b32_e32 v74, s8, v18
	v_or_b32_e32 v76, s8, v19
	v_or_b32_e32 v78, s8, v20
	v_or_b32_e32 v80, s8, v21
	v_or_b32_e32 v82, s8, v22
	v_or_b32_e32 v84, s8, v23
	v_or_b32_e32 v86, s8, v24
	v_or_b32_e32 v88, s8, v25
	v_or_b32_e32 v90, s8, v26
	v_or_b32_e32 v92, s8, v27
	v_or_b32_e32 v94, s8, v28
	v_or_b32_e32 v96, s8, v29
	v_or_b32_e32 v98, s8, v30
	v_or_b32_e32 v100, s8, v31
	v_or_b32_e32 v102, s8, v32
	v_or_b32_e32 v104, s8, v33
	v_or_b32_e32 v106, s8, v34
	v_or_b32_e32 v108, s8, v35
	v_or_b32_e32 v110, s8, v36
	v_or_b32_e32 v112, s8, v37
	v_or_b32_e32 v114, s8, v38
	v_or_b32_e32 v116, s8, v39
	v_or_b32_e32 v118, s8, v40
	v_or_b32_e32 v120, s8, v41
	v_or_b32_e32 v122, s8, v42
	s_ashr_i32 s9, s8, 31
	v_ashrrev_i32_e32 v11, 31, v10
	v_lshl_add_u64 v[54:55], v[2:3], 0, s[4:5]
	v_lshl_add_u64 v[8:9], v[4:5], 0, s[8:9]
	v_lshl_add_u64 v[58:59], v[6:7], 0, s[4:5]
	v_lshlrev_b64 v[56:57], 10, v[10:11]
	v_mad_i64_i32 v[60:61], s[4:5], v60, s12, v[54:55]
	v_mad_i64_i32 v[62:63], s[4:5], v62, s12, v[54:55]
	v_mad_i64_i32 v[64:65], s[4:5], v64, s12, v[54:55]
	v_mad_i64_i32 v[66:67], s[4:5], v66, s12, v[54:55]
	v_mad_i64_i32 v[68:69], s[4:5], v68, s12, v[54:55]
	v_mad_i64_i32 v[70:71], s[4:5], v70, s12, v[54:55]
	v_mad_i64_i32 v[72:73], s[4:5], v72, s12, v[54:55]
	v_mad_i64_i32 v[74:75], s[4:5], v74, s12, v[54:55]
	v_mad_i64_i32 v[76:77], s[4:5], v76, s12, v[54:55]
	v_mad_i64_i32 v[78:79], s[4:5], v78, s12, v[54:55]
	v_mad_i64_i32 v[80:81], s[4:5], v80, s12, v[54:55]
	v_mad_i64_i32 v[82:83], s[4:5], v82, s12, v[54:55]
	v_mad_i64_i32 v[84:85], s[4:5], v84, s12, v[54:55]
	v_mad_i64_i32 v[86:87], s[4:5], v86, s12, v[54:55]
	v_mad_i64_i32 v[88:89], s[4:5], v88, s12, v[54:55]
	v_mad_i64_i32 v[90:91], s[4:5], v90, s12, v[54:55]
	v_mad_i64_i32 v[92:93], s[4:5], v92, s12, v[54:55]
	v_mad_i64_i32 v[94:95], s[4:5], v94, s12, v[54:55]
	v_mad_i64_i32 v[96:97], s[4:5], v96, s12, v[54:55]
	v_mad_i64_i32 v[98:99], s[4:5], v98, s12, v[54:55]
	v_mad_i64_i32 v[100:101], s[4:5], v100, s12, v[54:55]
	v_mad_i64_i32 v[102:103], s[4:5], v102, s12, v[54:55]
	v_mad_i64_i32 v[104:105], s[4:5], v104, s12, v[54:55]
	v_mad_i64_i32 v[106:107], s[4:5], v106, s12, v[54:55]
	v_mad_i64_i32 v[108:109], s[4:5], v108, s12, v[54:55]
	v_mad_i64_i32 v[110:111], s[4:5], v110, s12, v[54:55]
	v_mad_i64_i32 v[112:113], s[4:5], v112, s12, v[54:55]
	v_mad_i64_i32 v[114:115], s[4:5], v114, s12, v[54:55]
	v_mad_i64_i32 v[116:117], s[4:5], v116, s12, v[54:55]
	v_mad_i64_i32 v[118:119], s[4:5], v118, s12, v[54:55]
	v_mad_i64_i32 v[120:121], s[4:5], v120, s12, v[54:55]
	v_mad_i64_i32 v[54:55], s[4:5], v122, s12, v[54:55]
	v_lshl_add_u64 v[122:123], v[8:9], 0, v[56:57]
	global_load_dword v11, v[60:61], off nt
	global_load_dword v56, v[62:63], off nt
	global_load_dword v57, v[64:65], off nt
	s_nop 0
	global_load_dword v60, v[66:67], off nt
	global_load_dword v61, v[68:69], off nt
	global_load_dword v62, v[70:71], off nt
	global_load_dword v63, v[72:73], off nt
	global_load_dword v64, v[74:75], off nt
	global_load_dword v65, v[76:77], off nt
	global_load_dword v66, v[78:79], off nt
	global_load_dword v67, v[80:81], off nt
	global_load_dword v68, v[82:83], off nt
	global_load_dword v69, v[84:85], off nt
	global_load_dword v70, v[86:87], off nt
	global_load_dword v71, v[88:89], off nt
	global_load_dword v72, v[90:91], off nt
	global_load_dword v73, v[92:93], off nt
	global_load_dword v74, v[94:95], off nt
	global_load_dword v75, v[96:97], off nt
	global_load_dword v76, v[98:99], off nt
	global_load_dword v77, v[100:101], off nt
	global_load_dword v78, v[102:103], off nt
	global_load_dword v79, v[104:105], off nt
	global_load_dword v80, v[106:107], off nt
	global_load_dword v81, v[108:109], off nt
	global_load_dword v82, v[110:111], off nt
	global_load_dword v83, v[112:113], off nt
	global_load_dword v84, v[114:115], off nt
	global_load_dword v85, v[116:117], off nt
	global_load_dword v86, v[118:119], off nt
	global_load_dword v87, v[120:121], off nt
	s_nop 0
	global_load_dword v54, v[54:55], off nt
	s_waitcnt vmcnt(30)
	ds_write2_b32 v45, v11, v56 offset1:66
	s_waitcnt vmcnt(28)
	ds_write2_b32 v45, v57, v60 offset0:132 offset1:198
	s_waitcnt vmcnt(26)
	ds_write2_b32 v46, v61, v62 offset0:8 offset1:74
	s_waitcnt vmcnt(24)
	ds_write2_b32 v46, v63, v64 offset0:140 offset1:206
	s_waitcnt vmcnt(22)
	ds_write2_b32 v47, v65, v66 offset0:16 offset1:82
	s_waitcnt vmcnt(20)
	ds_write2_b32 v47, v67, v68 offset0:148 offset1:214
	s_waitcnt vmcnt(18)
	ds_write2_b32 v48, v69, v70 offset0:24 offset1:90
	s_waitcnt vmcnt(16)
	ds_write2_b32 v48, v71, v72 offset0:156 offset1:222
	s_waitcnt vmcnt(14)
	ds_write2_b32 v49, v73, v74 offset0:32 offset1:98
	s_waitcnt vmcnt(12)
	ds_write2_b32 v49, v75, v76 offset0:164 offset1:230
	s_waitcnt vmcnt(10)
	ds_write2_b32 v50, v77, v78 offset0:40 offset1:106
	s_waitcnt vmcnt(8)
	ds_write2_b32 v50, v79, v80 offset0:172 offset1:238
	s_waitcnt vmcnt(6)
	ds_write2_b32 v51, v81, v82 offset0:48 offset1:114
	s_waitcnt vmcnt(4)
	ds_write2_b32 v51, v83, v84 offset0:180 offset1:246
	s_waitcnt vmcnt(2)
	ds_write2_b32 v52, v85, v86 offset0:56 offset1:122
	s_waitcnt vmcnt(0)
	ds_write2_b32 v52, v87, v54 offset0:188 offset1:254
	s_waitcnt lgkmcnt(0)
; #define GAS __attribute__((address_space(1)))
; #define LAS __attribute__((address_space(3)))
; #define LDS_WAIT() asm volatile("s_waitcnt lgkmcnt(0)" ::: "memory")
; __device__ __forceinline__ void quant8_item(const float* W, int K, int N, signed char* WT, const gu32* wmax, LAS float* scr, int item, int lane) {
;     ...
;     const int c = lane & 3;
; #pragma unroll
;     for (int j = 0; j < 2; ++j) { const int n = (lane >> 2) + 16 * j; const LAS float* sp = scr + (16 * c) * 33 + n;
;         const float am = __builtin_bit_cast(float, __hip_atomic_load((unsigned*)(wmax + n0 + n), RLX_AGENT));
;         const float inv = 127.0f / fmaxf(am, 1e-30f);
;         unsigned w[4];
; #pragma unroll
;         for (int q = 0; q < 4; ++q) { unsigned pk = 0;
; #pragma unroll
;             for (int i = 0; i < 4; ++i) pk |= ((unsigned)(int)rintf(sp[(4 * q + i) * 33] * inv) & 0xffu) << (8 * i);
;             w[q] = pk; }
;         *(GAS u32x4*)(WT + (size_t)(n0 + n) * K + k0 + 16 * c) = (u32x4){w[0], w[1], w[2], w[3]}; }
;     LDS_WAIT(); asm volatile("" ::: "memory");
	global_load_dword v11, v[58:59], off sc1
	ds_read2_b32 v[54:55], v44 offset1:33
	ds_read2_b32 v[56:57], v44 offset0:66 offset1:99
	ds_read2_b32 v[60:61], v44 offset0:132 offset1:165
	ds_read2_b32 v[62:63], v44 offset0:198 offset1:231
	ds_read2_b32 v[64:65], v53 offset0:8 offset1:41
	ds_read2_b32 v[66:67], v53 offset0:74 offset1:107
	ds_read2_b32 v[68:69], v53 offset0:140 offset1:173
	ds_read2_b32 v[70:71], v53 offset0:206 offset1:239
	v_add_u32_e32 v10, 16, v10
	s_add_i32 s2, s2, s3
	s_add_i32 s10, s10, s11
	s_cmpk_lt_i32 s2, 0x700
	s_waitcnt vmcnt(0)
	v_max_f32_e32 v11, v11, v11
	v_max_f32_e32 v11, 0xda24260, v11
	v_div_scale_f32 v72, s[4:5], v11, v11, s13
	v_rcp_f32_e32 v74, v72
	v_div_scale_f32 v73, vcc, s13, v11, s13
	v_fma_f32 v75, -v72, v74, 1.0
	v_fmac_f32_e32 v74, v75, v74
	v_mul_f32_e32 v75, v73, v74
	v_fma_f32 v76, -v72, v75, v73
	v_fmac_f32_e32 v75, v76, v74
	v_fma_f32 v72, -v72, v75, v73
	v_div_fmas_f32 v72, v72, v74, v75
	v_div_fixup_f32 v11, v72, v11, s13
	s_waitcnt lgkmcnt(7)
	v_mul_f32_e32 v55, v55, v11
	s_waitcnt lgkmcnt(5)
	v_mul_f32_e32 v61, v11, v61
	s_waitcnt lgkmcnt(3)
	v_mul_f32_e32 v65, v11, v65
	s_waitcnt lgkmcnt(1)
	v_mul_f32_e32 v69, v11, v69
	v_mul_f32_e32 v54, v54, v11
	v_mul_f32_e32 v56, v11, v56
	v_mul_f32_e32 v60, v11, v60
	v_mul_f32_e32 v62, v11, v62
	v_mul_f32_e32 v64, v11, v64
	v_mul_f32_e32 v66, v11, v66
	v_mul_f32_e32 v68, v11, v68
	s_waitcnt lgkmcnt(0)
	v_mul_f32_e32 v70, v11, v70
	v_rndne_f32_e32 v55, v55
	v_rndne_f32_e32 v61, v61
	v_rndne_f32_e32 v65, v65
	v_rndne_f32_e32 v69, v69
	v_mul_f32_e32 v57, v11, v57
	v_mul_f32_e32 v63, v11, v63
	v_mul_f32_e32 v67, v11, v67
	v_mul_f32_e32 v11, v11, v71
	v_rndne_f32_e32 v54, v54
	v_rndne_f32_e32 v56, v56
	v_rndne_f32_e32 v60, v60
	v_rndne_f32_e32 v62, v62
	v_rndne_f32_e32 v64, v64
	v_rndne_f32_e32 v66, v66
	v_rndne_f32_e32 v68, v68
	v_rndne_f32_e32 v70, v70
	v_cvt_i32_f32_e32 v55, v55
	v_cvt_i32_f32_e32 v61, v61
	v_cvt_i32_f32_e32 v65, v65
	v_cvt_i32_f32_e32 v69, v69
	v_rndne_f32_e32 v57, v57
	v_rndne_f32_e32 v63, v63
	v_rndne_f32_e32 v67, v67
	v_rndne_f32_e32 v11, v11
	v_cvt_i32_f32_e32 v54, v54
	v_cvt_i32_f32_sdwa v56, v56 dst_sel:WORD_1 dst_unused:UNUSED_PAD src0_sel:DWORD
	v_cvt_i32_f32_e32 v60, v60
	v_cvt_i32_f32_sdwa v62, v62 dst_sel:WORD_1 dst_unused:UNUSED_PAD src0_sel:DWORD
	v_cvt_i32_f32_e32 v64, v64
	v_cvt_i32_f32_sdwa v66, v66 dst_sel:WORD_1 dst_unused:UNUSED_PAD src0_sel:DWORD
	v_cvt_i32_f32_e32 v68, v68
	v_cvt_i32_f32_sdwa v70, v70 dst_sel:WORD_1 dst_unused:UNUSED_PAD src0_sel:DWORD
	v_cvt_i32_f32_sdwa v57, v57 dst_sel:BYTE_3 dst_unused:UNUSED_PAD src0_sel:DWORD
	v_cvt_i32_f32_sdwa v63, v63 dst_sel:BYTE_3 dst_unused:UNUSED_PAD src0_sel:DWORD
	v_cvt_i32_f32_sdwa v67, v67 dst_sel:BYTE_3 dst_unused:UNUSED_PAD src0_sel:DWORD
	v_cvt_i32_f32_sdwa v11, v11 dst_sel:BYTE_3 dst_unused:UNUSED_PAD src0_sel:DWORD
	v_lshlrev_b32_e32 v55, 8, v55
	v_lshlrev_b32_e32 v61, 8, v61
	v_lshlrev_b32_e32 v65, 8, v65
	v_lshlrev_b32_e32 v69, 8, v69
	v_and_b32_e32 v56, 0xff0000, v56
	v_and_b32_e32 v62, 0xff0000, v62
	v_and_b32_e32 v66, 0xff0000, v66
	v_and_b32_e32 v70, 0xff0000, v70
	v_perm_b32 v54, v55, v54, s14
	v_perm_b32 v55, v61, v60, s14
	v_perm_b32 v60, v65, v64, s14
	v_perm_b32 v61, v69, v68, s14
	v_or3_b32 v54, v54, v56, v57
	v_or3_b32 v55, v55, v62, v63
	v_or3_b32 v56, v60, v66, v67
	v_or3_b32 v57, v61, v70, v11
	global_store_dwordx4 v[122:123], v[54:57], off
	global_load_dword v68, v[58:59], off offset:64 sc1
	v_ashrrev_i32_e32 v11, 31, v10
	v_lshlrev_b64 v[10:11], 10, v[10:11]
	v_lshl_add_u64 v[54:55], v[8:9], 0, v[10:11]
	ds_read2_b32 v[8:9], v44 offset0:16 offset1:49
	ds_read2_b32 v[10:11], v44 offset0:82 offset1:115
	ds_read2_b32 v[56:57], v44 offset0:148 offset1:181
	ds_read2_b32 v[58:59], v44 offset0:214 offset1:247
	ds_read2_b32 v[60:61], v53 offset0:24 offset1:57
	ds_read2_b32 v[62:63], v53 offset0:90 offset1:123
	ds_read2_b32 v[64:65], v53 offset0:156 offset1:189
	ds_read2_b32 v[66:67], v53 offset0:222 offset1:255
	s_waitcnt vmcnt(0)
	v_max_f32_e32 v68, v68, v68
	v_max_f32_e32 v68, 0xda24260, v68
	v_div_scale_f32 v69, s[4:5], v68, v68, s13
	v_rcp_f32_e32 v71, v69
	v_div_scale_f32 v70, vcc, s13, v68, s13
	v_fma_f32 v72, -v69, v71, 1.0
	v_fmac_f32_e32 v71, v72, v71
	v_mul_f32_e32 v72, v70, v71
	v_fma_f32 v73, -v69, v72, v70
	v_fmac_f32_e32 v72, v73, v71
	v_fma_f32 v69, -v69, v72, v70
	v_div_fmas_f32 v69, v69, v71, v72
	v_div_fixup_f32 v68, v69, v68, s13
	s_waitcnt lgkmcnt(7)
	v_mul_f32_e32 v9, v9, v68
	s_waitcnt lgkmcnt(5)
	v_mul_f32_e32 v57, v68, v57
	s_waitcnt lgkmcnt(3)
	v_mul_f32_e32 v61, v68, v61
	s_waitcnt lgkmcnt(1)
	v_mul_f32_e32 v65, v68, v65
	v_mul_f32_e32 v8, v8, v68
	v_mul_f32_e32 v10, v68, v10
	v_mul_f32_e32 v56, v68, v56
	v_mul_f32_e32 v58, v68, v58
	v_mul_f32_e32 v60, v68, v60
	v_mul_f32_e32 v62, v68, v62
	v_mul_f32_e32 v64, v68, v64
	s_waitcnt lgkmcnt(0)
	v_mul_f32_e32 v66, v68, v66
	v_rndne_f32_e32 v9, v9
	v_rndne_f32_e32 v57, v57
	v_rndne_f32_e32 v61, v61
	v_rndne_f32_e32 v65, v65
	v_mul_f32_e32 v11, v68, v11
	v_mul_f32_e32 v59, v68, v59
	v_mul_f32_e32 v63, v68, v63
	v_mul_f32_e32 v67, v68, v67
	v_rndne_f32_e32 v8, v8
	v_rndne_f32_e32 v10, v10
	v_rndne_f32_e32 v56, v56
	v_rndne_f32_e32 v58, v58
	v_rndne_f32_e32 v60, v60
	v_rndne_f32_e32 v62, v62
	v_rndne_f32_e32 v64, v64
	v_rndne_f32_e32 v66, v66
	v_cvt_i32_f32_e32 v9, v9
	v_cvt_i32_f32_e32 v57, v57
	v_cvt_i32_f32_e32 v61, v61
	v_cvt_i32_f32_e32 v65, v65
	v_rndne_f32_e32 v11, v11
	v_rndne_f32_e32 v59, v59
	v_rndne_f32_e32 v63, v63
	v_rndne_f32_e32 v67, v67
	v_cvt_i32_f32_e32 v8, v8
	v_cvt_i32_f32_sdwa v10, v10 dst_sel:WORD_1 dst_unused:UNUSED_PAD src0_sel:DWORD
	v_cvt_i32_f32_e32 v56, v56
	v_cvt_i32_f32_sdwa v58, v58 dst_sel:WORD_1 dst_unused:UNUSED_PAD src0_sel:DWORD
	v_cvt_i32_f32_e32 v60, v60
	v_cvt_i32_f32_sdwa v62, v62 dst_sel:WORD_1 dst_unused:UNUSED_PAD src0_sel:DWORD
	v_cvt_i32_f32_e32 v64, v64
	v_cvt_i32_f32_sdwa v66, v66 dst_sel:WORD_1 dst_unused:UNUSED_PAD src0_sel:DWORD
	v_cvt_i32_f32_sdwa v11, v11 dst_sel:BYTE_3 dst_unused:UNUSED_PAD src0_sel:DWORD
	v_cvt_i32_f32_sdwa v59, v59 dst_sel:BYTE_3 dst_unused:UNUSED_PAD src0_sel:DWORD
	v_cvt_i32_f32_sdwa v63, v63 dst_sel:BYTE_3 dst_unused:UNUSED_PAD src0_sel:DWORD
	v_cvt_i32_f32_sdwa v67, v67 dst_sel:BYTE_3 dst_unused:UNUSED_PAD src0_sel:DWORD
	v_lshlrev_b32_e32 v9, 8, v9
	v_lshlrev_b32_e32 v57, 8, v57
	v_lshlrev_b32_e32 v61, 8, v61
	v_lshlrev_b32_e32 v65, 8, v65
	v_and_b32_e32 v10, 0xff0000, v10
	v_and_b32_e32 v58, 0xff0000, v58
	v_and_b32_e32 v62, 0xff0000, v62
	v_and_b32_e32 v66, 0xff0000, v66
	v_perm_b32 v8, v9, v8, s14
	v_perm_b32 v9, v57, v56, s14
	v_perm_b32 v56, v61, v60, s14
	v_perm_b32 v57, v65, v64, s14
	v_or3_b32 v8, v8, v10, v11
	v_or3_b32 v9, v9, v58, v59
	v_or3_b32 v10, v56, v62, v63
	v_or3_b32 v11, v57, v66, v67
	global_store_dwordx4 v[54:55], v[8:11], off
	s_waitcnt lgkmcnt(0)
	s_cbranch_scc1 .LBB0_132

; #define CONV_LOAD(ci, rg) do { const int nblk_ = (ci).N / 32, kb_ = (ci).item / nblk_, nb_ = (ci).item % nblk_; const float* wp_ = (ci).W + (size_t)(64 * kb_ + (F.lane >> 5)) * (ci).N + 32 * nb_ + (F.lane & 31); \
;         _Pragma("unroll") for (int i_ = 0; i_ < 32; ++i_) rg[i_] = wp_[(size_t)(2 * i_) * (ci).N]; } while (0)
; __device__ __forceinline__ void conv_layer(Frame& F, const Args& args, int layer) {
;     ...
;     ConvItem cur; float rg[32];
;     if (gw < NIT) { cur = decode(gw); CONV_LOAD(cur, rg); }
.LBB0_1322:
	s_lshl_b32 s16, s16, 14
	s_add_i32 s24, s16, 0
	s_lshr_b32 s16, s56, 5
	v_cvt_f32_u32_e32 v2, s16
	s_sub_i32 s41, 0, s16
	s_abs_i32 s39, s52
	s_lshl_b32 s47, s28, 3
	v_rcp_iflag_f32_e32 v2, v2
	s_ashr_i32 s25, s52, 31
	v_bfe_u32 v12, v3, 5, 1
	v_readlane_b32 s60, v253, 18
	v_mul_f32_e32 v2, 0x4f7ffffe, v2
	v_cvt_u32_f32_e32 v2, v2
	s_mul_i32 s58, s38, 0x7000000
	v_readlane_b32 s72, v253, 30
	s_mul_hi_u32 s57, s38, 0x7000000
	v_readfirstlane_b32 s42, v2
	s_mul_i32 s41, s41, s42
	s_mul_hi_u32 s41, s42, s41
	s_add_i32 s42, s42, s41
	s_mul_hi_u32 s41, s39, s42
	s_mul_i32 s42, s41, s16
	s_sub_i32 s39, s39, s42
	s_add_i32 s42, s41, 1
	s_sub_i32 s43, s39, s16
	s_cmp_ge_u32 s39, s16
	s_cselect_b32 s41, s42, s41
	s_cselect_b32 s39, s43, s39
	s_add_i32 s42, s41, 1
	s_cmp_ge_u32 s39, s16
	s_cselect_b32 s39, s42, s41
	s_xor_b32 s39, s39, s25
	s_sub_i32 s25, s39, s25
	s_lshl_b32 s39, s25, 6
	v_or_b32_e32 v2, s39, v12
	s_ashr_i32 s39, s39, 31
	s_mul_i32 s39, s39, s56
	v_mad_u64_u32 v[4:5], s[42:43], v2, s56, 0
	v_add_u32_e32 v5, s39, v5
	s_mul_i32 s25, s25, s16
	v_lshl_add_u64 v[4:5], v[4:5], 2, s[12:13]
	s_sub_i32 s12, s52, s25
	s_lshl_b32 s12, s12, 5
	s_ashr_i32 s13, s12, 31
	v_and_b32_e32 v2, 31, v3
	v_lshl_add_u64 v[4:5], s[12:13], 2, v[4:5]
	v_lshlrev_b32_e32 v66, 2, v2
	v_lshl_add_u64 v[4:5], v[4:5], 0, v[66:67]
	s_lshl_b32 s16, s56, 1
	v_lshl_add_u64 v[6:7], s[16:17], 2, v[4:5]
	s_lshl_b32 s16, s56, 2
	global_load_dword v9, v[4:5], off nt
	global_load_dword v10, v[6:7], off nt
	v_lshl_add_u64 v[6:7], s[16:17], 2, v[4:5]
	s_mul_i32 s16, s56, 6
	global_load_dword v22, v[6:7], off nt
	v_lshl_add_u64 v[6:7], s[16:17], 2, v[4:5]
	s_lshl_b32 s16, s56, 3
	global_load_dword v24, v[6:7], off nt
	v_lshl_add_u64 v[6:7], s[16:17], 2, v[4:5]
	s_mul_i32 s16, s56, 10
	global_load_dword v11, v[6:7], off nt
	v_lshl_add_u64 v[6:7], s[16:17], 2, v[4:5]
	s_mul_i32 s16, s56, 12
	global_load_dword v23, v[6:7], off nt
	v_lshl_add_u64 v[6:7], s[16:17], 2, v[4:5]
	s_mul_i32 s16, s56, 14
	global_load_dword v25, v[6:7], off nt
	v_lshl_add_u64 v[6:7], s[16:17], 2, v[4:5]
	s_lshl_b32 s16, s56, 4
	global_load_dword v26, v[6:7], off nt
	v_lshl_add_u64 v[6:7], s[16:17], 2, v[4:5]
	s_mul_i32 s16, s56, 18
	global_load_dword v27, v[6:7], off nt
	v_lshl_add_u64 v[6:7], s[16:17], 2, v[4:5]
	s_mul_i32 s16, s56, 20
	global_load_dword v28, v[6:7], off nt
	v_lshl_add_u64 v[6:7], s[16:17], 2, v[4:5]
	s_mul_i32 s16, s56, 22
	global_load_dword v29, v[6:7], off nt
	v_lshl_add_u64 v[6:7], s[16:17], 2, v[4:5]
	s_mul_i32 s16, s56, 24
	global_load_dword v30, v[6:7], off nt
	v_lshl_add_u64 v[6:7], s[16:17], 2, v[4:5]
	s_mul_i32 s16, s56, 26
	global_load_dword v31, v[6:7], off nt
	v_lshl_add_u64 v[6:7], s[16:17], 2, v[4:5]
	s_mul_i32 s16, s56, 28
	global_load_dword v32, v[6:7], off nt
	v_lshl_add_u64 v[6:7], s[16:17], 2, v[4:5]
	s_mul_i32 s16, s56, 30
	global_load_dword v33, v[6:7], off nt
	v_lshl_add_u64 v[6:7], s[16:17], 2, v[4:5]
	s_lshl_b32 s16, s56, 5
	global_load_dword v34, v[6:7], off nt
	v_lshl_add_u64 v[6:7], s[16:17], 2, v[4:5]
	s_mul_i32 s16, s56, 34
	global_load_dword v35, v[6:7], off nt
	v_lshl_add_u64 v[6:7], s[16:17], 2, v[4:5]
	s_mul_i32 s16, s56, 36
	global_load_dword v36, v[6:7], off nt
	v_lshl_add_u64 v[6:7], s[16:17], 2, v[4:5]
	s_mul_i32 s16, s56, 38
	global_load_dword v37, v[6:7], off nt
	v_lshl_add_u64 v[6:7], s[16:17], 2, v[4:5]
	s_mul_i32 s16, s56, 40
	global_load_dword v38, v[6:7], off nt
	v_lshl_add_u64 v[6:7], s[16:17], 2, v[4:5]
	s_mul_i32 s16, s56, 42
	global_load_dword v39, v[6:7], off nt
	v_lshl_add_u64 v[6:7], s[16:17], 2, v[4:5]
	s_mul_i32 s16, s56, 44
	global_load_dword v40, v[6:7], off nt
	v_lshl_add_u64 v[6:7], s[16:17], 2, v[4:5]
	s_mul_i32 s16, s56, 46
	global_load_dword v42, v[6:7], off nt
	v_lshl_add_u64 v[6:7], s[16:17], 2, v[4:5]
	s_mul_i32 s16, s56, 48
	global_load_dword v43, v[6:7], off nt
	v_lshl_add_u64 v[6:7], s[16:17], 2, v[4:5]
	s_mul_i32 s16, s56, 50
	global_load_dword v44, v[6:7], off nt
	v_lshl_add_u64 v[6:7], s[16:17], 2, v[4:5]
	s_mul_i32 s16, s56, 52
	global_load_dword v45, v[6:7], off nt
	v_lshl_add_u64 v[6:7], s[16:17], 2, v[4:5]
	s_mul_i32 s16, s56, 54
	global_load_dword v46, v[6:7], off nt
	v_lshl_add_u64 v[6:7], s[16:17], 2, v[4:5]
	s_mul_i32 s16, s56, 56
	global_load_dword v47, v[6:7], off nt
	v_lshl_add_u64 v[6:7], s[16:17], 2, v[4:5]
	s_mul_i32 s16, s56, 58
	global_load_dword v48, v[6:7], off nt
	v_lshl_add_u64 v[6:7], s[16:17], 2, v[4:5]
	s_mul_i32 s16, s56, 60
	global_load_dword v49, v[6:7], off nt
	v_lshl_add_u64 v[6:7], s[16:17], 2, v[4:5]
	s_mul_i32 s16, s56, 62
	v_lshl_add_u64 v[4:5], s[16:17], 2, v[4:5]
	global_load_dword v50, v[6:7], off nt
	s_lshl_b32 s16, s0, 22
	global_load_dword v4, v[4:5], off nt
	v_readlane_b32 s73, v253, 31
	s_add_u32 s0, s72, s58
	v_readlane_b32 s64, v253, 22
	v_writelane_b32 v255, s0, 28
	s_addc_u32 s86, s73, s57
	v_readlane_b32 s0, v253, 36
	s_mul_hi_u32 s59, s38, 0xb00000
	v_readlane_b32 s61, v253, 19
	v_readlane_b32 s62, v253, 20
	v_readlane_b32 s63, v253, 21
	v_readlane_b32 s65, v253, 23
	v_readlane_b32 s66, v253, 24
	v_readlane_b32 s67, v253, 25
	v_readlane_b32 s68, v253, 26
	v_readlane_b32 s69, v253, 27
	v_readlane_b32 s70, v253, 28
	v_readlane_b32 s71, v253, 29
	v_readlane_b32 s74, v253, 32
	v_readlane_b32 s75, v253, 33
	s_add_u32 s0, s64, s0
	v_lshlrev_b32_e32 v6, 4, v3
	s_addc_u32 s1, s65, s59
	v_readlane_b32 s60, v253, 2
	v_and_b32_e32 v6, 48, v6
	v_readlane_b32 s70, v253, 12
	v_bfe_u32 v13, v3, 2, 4
	v_mul_u32_u24_e32 v8, 0x84, v6
	v_and_b32_e32 v14, 60, v3
	v_bfe_u32 v16, v3, 3, 3
	v_lshlrev_b32_e32 v3, 3, v3
	v_readlane_b32 s71, v253, 13
	s_add_u32 s38, s70, s16
	v_add3_u32 v14, s24, v8, v14
	v_and_b32_e32 v8, 56, v3
	v_add_u32_e32 v5, s24, v66
	v_mul_u32_u24_e32 v21, 0x84, v12
	v_writelane_b32 v255, s0, 19
	v_readlane_b32 s61, v253, 3
	v_readlane_b32 s74, v253, 16
	v_readlane_b32 s75, v253, 17
	s_addc_u32 s39, s71, 0
	v_mul_u32_u24_e32 v3, 0x84, v8
	v_lshlrev_b32_e32 v17, 2, v16
	s_add_i32 s16, s47, s51
	v_writelane_b32 v255, s1, 20
	v_readlane_b32 s63, v253, 5
	v_readlane_b32 s64, v253, 6
	v_readlane_b32 s65, v253, 7
	v_readlane_b32 s67, v253, 9
	v_readlane_b32 s68, v253, 10
	v_mov_b32_e32 v7, v67
	v_or_b32_e32 v15, 16, v13
	v_add3_u32 v17, s24, v3, v17
	v_or_b32_e32 v18, 8, v16
	v_or_b32_e32 v19, 16, v16
	v_or_b32_e32 v20, 24, v16
	s_add_i32 s29, s16, 0xffff8e00
	v_mov_b32_e32 v41, s40
	v_lshlrev_b32_e32 v66, 2, v2
	v_add_u32_e32 v21, v5, v21
	v_lshlrev_b32_e32 v8, 1, v8
	s_mov_b32 s61, 0x8000
	s_mov_b64 s[74:75], 0x30080
	v_readlane_b32 s62, v253, 4
	v_readlane_b32 s66, v253, 8
	v_readlane_b32 s69, v253, 11
	v_readlane_b32 s72, v253, 14
	v_readlane_b32 s73, v253, 15
	s_branch .LBB0_1324

; #define CONV_LOAD(ci, rg) do { const int nblk_ = (ci).N / 32, kb_ = (ci).item / nblk_, nb_ = (ci).item % nblk_; const float* wp_ = (ci).W + (size_t)(64 * kb_ + (F.lane >> 5)) * (ci).N + 32 * nb_ + (F.lane & 31); \
;         _Pragma("unroll") for (int i_ = 0; i_ < 32; ++i_) rg[i_] = wp_[(size_t)(2 * i_) * (ci).N]; } while (0)
; __device__ __forceinline__ void conv_layer(Frame& F, const Args& args, int layer) {
;     ...
;     for (int it = gw; it < NIT; it += NGW) {
;         ConvItem nxt; float nrg[32]; const bool hn = it + NGW < NIT;
;         if (hn) { nxt = decode(it + NGW); CONV_LOAD(nxt, nrg); }
.LBB0_1345:
	s_lshr_b32 s16, s67, 5
	v_cvt_f32_u32_e32 v2, s16
	s_sub_i32 s72, 0, s16
	s_abs_i32 s25, s63
	s_ashr_i32 s24, s63, 31
	v_rcp_iflag_f32_e32 v2, v2
	s_nop 0
	v_mul_f32_e32 v2, 0x4f7ffffe, v2
	v_cvt_u32_f32_e32 v2, v2
	s_nop 0
	v_readfirstlane_b32 s73, v2
	s_mul_i32 s72, s72, s73
	s_mul_hi_u32 s72, s73, s72
	s_add_i32 s73, s73, s72
	s_mul_hi_u32 s72, s25, s73
	s_mul_i32 s73, s72, s16
	s_sub_i32 s25, s25, s73
	s_add_i32 s73, s72, 1
	s_sub_i32 s77, s25, s16
	s_cmp_ge_u32 s25, s16
	s_cselect_b32 s72, s73, s72
	s_cselect_b32 s25, s77, s25
	s_add_i32 s73, s72, 1
	s_cmp_ge_u32 s25, s16
	s_cselect_b32 s25, s73, s72
	s_xor_b32 s25, s25, s24
	s_sub_i32 s24, s25, s24
	s_mul_i32 s16, s24, s16
	s_lshl_b32 s24, s24, 6
	v_or_b32_e32 v2, s24, v12
	s_ashr_i32 s24, s24, 31
	s_sub_i32 s16, s63, s16
	s_mul_i32 s72, s24, s67
	v_mad_u64_u32 v[2:3], s[24:25], v2, s67, 0
	v_add_u32_e32 v3, s72, v3
	s_lshl_b32 s24, s16, 5
	v_lshl_add_u64 v[2:3], v[2:3], 2, s[44:45]
	s_ashr_i32 s25, s24, 31
	v_lshl_add_u64 v[2:3], s[24:25], 2, v[2:3]
	v_lshl_add_u64 v[2:3], v[2:3], 0, v[66:67]
	s_lshl_b32 s16, s67, 1
	v_lshl_add_u64 v[52:53], s[16:17], 2, v[2:3]
	s_lshl_b32 s16, s67, 2
	v_lshl_add_u64 v[54:55], s[16:17], 2, v[2:3]
	s_mul_i32 s16, s67, 6
	global_load_dword v51, v[2:3], off nt
	s_nop 0
	global_load_dword v52, v[52:53], off nt
	s_nop 0
	global_load_dword v53, v[54:55], off nt
	v_lshl_add_u64 v[54:55], s[16:17], 2, v[2:3]
	s_lshl_b32 s16, s67, 3
	v_lshl_add_u64 v[56:57], s[16:17], 2, v[2:3]
	s_mul_i32 s16, s67, 10
	global_load_dword v54, v[54:55], off nt
	s_nop 0
	global_load_dword v55, v[56:57], off nt
	v_lshl_add_u64 v[56:57], s[16:17], 2, v[2:3]
	s_mul_i32 s16, s67, 12
	v_lshl_add_u64 v[58:59], s[16:17], 2, v[2:3]
	s_mul_i32 s16, s67, 14
	global_load_dword v56, v[56:57], off nt
	s_nop 0
	global_load_dword v57, v[58:59], off nt
	v_lshl_add_u64 v[58:59], s[16:17], 2, v[2:3]
	s_lshl_b32 s16, s67, 4
	v_lshl_add_u64 v[60:61], s[16:17], 2, v[2:3]
	s_mul_i32 s16, s67, 18
	global_load_dword v58, v[58:59], off nt
	s_nop 0
	global_load_dword v59, v[60:61], off nt
	v_lshl_add_u64 v[60:61], s[16:17], 2, v[2:3]
	s_mul_i32 s16, s67, 20
	v_lshl_add_u64 v[62:63], s[16:17], 2, v[2:3]
	s_mul_i32 s16, s67, 22
	global_load_dword v60, v[60:61], off nt
	s_nop 0
	global_load_dword v61, v[62:63], off nt
	v_lshl_add_u64 v[62:63], s[16:17], 2, v[2:3]
	s_mul_i32 s16, s67, 24
	v_lshl_add_u64 v[64:65], s[16:17], 2, v[2:3]
	s_mul_i32 s16, s67, 26
	global_load_dword v62, v[62:63], off nt
	s_nop 0
	global_load_dword v63, v[64:65], off nt
	v_lshl_add_u64 v[64:65], s[16:17], 2, v[2:3]
	s_mul_i32 s16, s67, 28
	v_lshl_add_u64 v[68:69], s[16:17], 2, v[2:3]
	s_mul_i32 s16, s67, 30
	global_load_dword v64, v[64:65], off nt
	s_nop 0
	global_load_dword v65, v[68:69], off nt
	v_lshl_add_u64 v[68:69], s[16:17], 2, v[2:3]
	s_lshl_b32 s16, s67, 5
	v_lshl_add_u64 v[70:71], s[16:17], 2, v[2:3]
	s_mul_i32 s16, s67, 34
	global_load_dword v68, v[68:69], off nt
	s_nop 0
	global_load_dword v69, v[70:71], off nt
	v_lshl_add_u64 v[70:71], s[16:17], 2, v[2:3]
	s_mul_i32 s16, s67, 36
	v_lshl_add_u64 v[72:73], s[16:17], 2, v[2:3]
	s_mul_i32 s16, s67, 38
	global_load_dword v70, v[70:71], off nt
	s_nop 0
	global_load_dword v71, v[72:73], off nt
	v_lshl_add_u64 v[72:73], s[16:17], 2, v[2:3]
	s_mul_i32 s16, s67, 40
	v_lshl_add_u64 v[74:75], s[16:17], 2, v[2:3]
	s_mul_i32 s16, s67, 42
	global_load_dword v72, v[72:73], off nt
	s_nop 0
	global_load_dword v73, v[74:75], off nt
	v_lshl_add_u64 v[74:75], s[16:17], 2, v[2:3]
	s_mul_i32 s16, s67, 44
	v_lshl_add_u64 v[76:77], s[16:17], 2, v[2:3]
	s_mul_i32 s16, s67, 46
	global_load_dword v74, v[74:75], off nt
	s_nop 0
	global_load_dword v75, v[76:77], off nt
	v_lshl_add_u64 v[76:77], s[16:17], 2, v[2:3]
	s_mul_i32 s16, s67, 48
	v_lshl_add_u64 v[78:79], s[16:17], 2, v[2:3]
	s_mul_i32 s16, s67, 50
	global_load_dword v76, v[76:77], off nt
	s_nop 0
	global_load_dword v77, v[78:79], off nt
	v_lshl_add_u64 v[78:79], s[16:17], 2, v[2:3]
	s_mul_i32 s16, s67, 52
	v_lshl_add_u64 v[80:81], s[16:17], 2, v[2:3]
	s_mul_i32 s16, s67, 54
	global_load_dword v78, v[78:79], off nt
	s_nop 0
	global_load_dword v79, v[80:81], off nt
	v_lshl_add_u64 v[80:81], s[16:17], 2, v[2:3]
	s_mul_i32 s16, s67, 56
	v_lshl_add_u64 v[82:83], s[16:17], 2, v[2:3]
	s_mul_i32 s16, s67, 58
	global_load_dword v80, v[80:81], off nt
	s_nop 0
	global_load_dword v81, v[82:83], off nt
	v_lshl_add_u64 v[82:83], s[16:17], 2, v[2:3]
	s_mul_i32 s16, s67, 60
	v_lshl_add_u64 v[84:85], s[16:17], 2, v[2:3]
	s_mul_i32 s16, s67, 62
	v_lshl_add_u64 v[2:3], s[16:17], 2, v[2:3]
	global_load_dword v82, v[82:83], off nt
	s_nop 0
	global_load_dword v83, v[84:85], off nt
	v_mov_b32_e32 v85, s69
	global_load_dword v84, v[2:3], off nt

; #define LAS __attribute__((address_space(3)))
; #define LDS_WAIT() asm volatile("s_waitcnt lgkmcnt(0)" ::: "memory")
; __device__ __forceinline__ void quant8_item(const float* W, int K, int N, signed char* WT, const gu32* wmax, LAS float* scr, int item, int lane) {
;     const int nblk = N / 32, kb = item / nblk, nb = item % nblk, k0 = 64 * kb, n0 = 32 * nb;
; #pragma unroll
;     for (int i = 0; i < 32; ++i) { const int kk = 2 * i + (lane >> 5); scr[kk * 33 + (lane & 31)] = W[(size_t)(k0 + kk) * N + n0 + (lane & 31)]; }
;     LDS_WAIT(); asm volatile("" ::: "memory");
;     const int c = lane & 3;
; #pragma unroll
;     for (int j = 0; j < 2; ++j) { const int n = (lane >> 2) + 16 * j; const LAS float* sp = scr + (16 * c) * 33 + n;
;         const float am = __builtin_bit_cast(float, __hip_atomic_load((unsigned*)(wmax + n0 + n), RLX_AGENT));
.LBB0_1354:
	s_mul_hi_i32 s0, s6, 0x92492493
	s_add_i32 s0, s0, s6
	s_lshr_b32 s1, s0, 31
	s_ashr_i32 s0, s0, 6
	s_add_i32 s0, s0, s1
	s_lshl_b32 s2, s0, 6
	s_mulk_i32 s0, 0xf200
	s_add_i32 s0, s10, s0
	s_ashr_i32 s1, s0, 31
	s_lshl_b64 s[8:9], s[0:1], 2
	v_lshl_add_u64 v[2:3], v[6:7], 0, s[8:9]
	v_or_b32_e32 v4, s2, v20
	v_mad_i64_i32 v[4:5], s[12:13], v4, s4, v[2:3]
	global_load_dword v56, v[4:5], off nt
	v_or_b32_e32 v4, s2, v21
	v_mad_i64_i32 v[4:5], s[12:13], v4, s4, v[2:3]
	global_load_dword v57, v[4:5], off nt
	v_lshl_add_u64 v[14:15], v[10:11], 0, s[8:9]
	s_ashr_i32 s3, s2, 31
	v_add_u32_e32 v55, 0x400, v53
	s_add_i32 s6, s6, s7
	s_add_i32 s10, s10, s11
	s_cmpk_lt_i32 s6, 0x700
	v_or_b32_e32 v4, s2, v22
	v_mad_i64_i32 v[4:5], s[12:13], v4, s4, v[2:3]
	global_load_dword v58, v[4:5], off nt
	v_or_b32_e32 v4, s2, v23
	v_mad_i64_i32 v[4:5], s[12:13], v4, s4, v[2:3]
	global_load_dword v59, v[4:5], off nt
	v_or_b32_e32 v4, s2, v24
	v_mad_i64_i32 v[4:5], s[12:13], v4, s4, v[2:3]
	global_load_dword v60, v[4:5], off nt
	v_or_b32_e32 v4, s2, v25
	v_mad_i64_i32 v[4:5], s[12:13], v4, s4, v[2:3]
	global_load_dword v61, v[4:5], off nt
	v_or_b32_e32 v4, s2, v26
	v_mad_i64_i32 v[4:5], s[12:13], v4, s4, v[2:3]
	global_load_dword v62, v[4:5], off nt
	v_or_b32_e32 v4, s2, v27
	v_mad_i64_i32 v[4:5], s[12:13], v4, s4, v[2:3]
	global_load_dword v63, v[4:5], off nt
	v_or_b32_e32 v4, s2, v28
	v_mad_i64_i32 v[4:5], s[12:13], v4, s4, v[2:3]
	global_load_dword v64, v[4:5], off nt
	v_or_b32_e32 v4, s2, v29
	v_mad_i64_i32 v[4:5], s[12:13], v4, s4, v[2:3]
	global_load_dword v65, v[4:5], off nt
	v_or_b32_e32 v4, s2, v30
	v_mad_i64_i32 v[4:5], s[12:13], v4, s4, v[2:3]
	global_load_dword v68, v[4:5], off nt
	v_or_b32_e32 v4, s2, v31
	v_mad_i64_i32 v[4:5], s[12:13], v4, s4, v[2:3]
	global_load_dword v69, v[4:5], off nt
	v_or_b32_e32 v4, s2, v32
	v_mad_i64_i32 v[4:5], s[12:13], v4, s4, v[2:3]
	global_load_dword v70, v[4:5], off nt
	v_or_b32_e32 v4, s2, v33
	v_mad_i64_i32 v[4:5], s[12:13], v4, s4, v[2:3]
	global_load_dword v71, v[4:5], off nt
	v_or_b32_e32 v4, s2, v34
	v_mad_i64_i32 v[4:5], s[12:13], v4, s4, v[2:3]
	global_load_dword v72, v[4:5], off nt
	v_or_b32_e32 v4, s2, v35
	v_mad_i64_i32 v[4:5], s[12:13], v4, s4, v[2:3]
	global_load_dword v73, v[4:5], off nt
	v_or_b32_e32 v4, s2, v36
	v_mad_i64_i32 v[4:5], s[12:13], v4, s4, v[2:3]
	global_load_dword v74, v[4:5], off nt
	v_or_b32_e32 v4, s2, v37
	v_mad_i64_i32 v[4:5], s[12:13], v4, s4, v[2:3]
	global_load_dword v75, v[4:5], off nt
	v_or_b32_e32 v4, s2, v38
	v_mad_i64_i32 v[4:5], s[12:13], v4, s4, v[2:3]
	global_load_dword v76, v[4:5], off nt
	v_or_b32_e32 v4, s2, v39
	v_mad_i64_i32 v[4:5], s[12:13], v4, s4, v[2:3]
	global_load_dword v77, v[4:5], off nt
	v_or_b32_e32 v4, s2, v40
	v_mad_i64_i32 v[4:5], s[12:13], v4, s4, v[2:3]
	global_load_dword v78, v[4:5], off nt
	v_or_b32_e32 v4, s2, v41
	v_mad_i64_i32 v[4:5], s[12:13], v4, s4, v[2:3]
	global_load_dword v79, v[4:5], off nt
	v_or_b32_e32 v4, s2, v42
	v_mad_i64_i32 v[4:5], s[12:13], v4, s4, v[2:3]
	global_load_dword v80, v[4:5], off nt
	v_or_b32_e32 v4, s2, v43
	v_mad_i64_i32 v[4:5], s[12:13], v4, s4, v[2:3]
	global_load_dword v81, v[4:5], off nt
	v_or_b32_e32 v4, s2, v44
	v_mad_i64_i32 v[4:5], s[12:13], v4, s4, v[2:3]
	global_load_dword v82, v[4:5], off nt
	v_or_b32_e32 v4, s2, v45
	v_mad_i64_i32 v[4:5], s[12:13], v4, s4, v[2:3]
	global_load_dword v83, v[4:5], off nt
	v_or_b32_e32 v4, s2, v46
	v_mad_i64_i32 v[4:5], s[12:13], v4, s4, v[2:3]
	global_load_dword v84, v[4:5], off nt
	v_or_b32_e32 v4, s2, v47
	v_mad_i64_i32 v[4:5], s[12:13], v4, s4, v[2:3]
	global_load_dword v85, v[4:5], off nt
	v_or_b32_e32 v4, s2, v48
	v_mad_i64_i32 v[4:5], s[12:13], v4, s4, v[2:3]
	global_load_dword v86, v[4:5], off nt
	v_or_b32_e32 v4, s2, v49
	v_mad_i64_i32 v[4:5], s[12:13], v4, s4, v[2:3]
	global_load_dword v87, v[4:5], off nt
	v_or_b32_e32 v4, s2, v50
	v_mad_i64_i32 v[4:5], s[12:13], v4, s4, v[2:3]
	global_load_dword v88, v[4:5], off nt
	v_or_b32_e32 v5, s2, v51
	v_mad_i64_i32 v[2:3], s[12:13], v5, s4, v[2:3]
	global_load_dword v89, v[2:3], off nt
	global_load_dword v90, v[14:15], off sc1
	global_load_dword v91, v[14:15], off offset:64 sc1
	v_add_u32_e32 v13, 0x400, v54
	s_waitcnt vmcnt(32)
	ds_write2_b32 v54, v56, v57 offset1:66
	s_waitcnt vmcnt(30)
	ds_write2_b32 v54, v58, v59 offset0:132 offset1:198
	s_waitcnt vmcnt(28)
	ds_write2_b32 v13, v60, v61 offset0:8 offset1:74
	s_waitcnt vmcnt(26)
	ds_write2_b32 v13, v62, v63 offset0:140 offset1:206
	v_add_u32_e32 v13, 0x800, v54
	s_waitcnt vmcnt(24)
	ds_write2_b32 v13, v64, v65 offset0:16 offset1:82
	s_waitcnt vmcnt(22)
	ds_write2_b32 v13, v68, v69 offset0:148 offset1:214
	v_add_u32_e32 v13, 0xc00, v54
	s_waitcnt vmcnt(20)
	ds_write2_b32 v13, v70, v71 offset0:24 offset1:90
	s_waitcnt vmcnt(18)
	ds_write2_b32 v13, v72, v73 offset0:156 offset1:222
	v_add_u32_e32 v13, 0x1000, v54
	s_waitcnt vmcnt(16)
	ds_write2_b32 v13, v74, v75 offset0:32 offset1:98
	s_waitcnt vmcnt(14)
	ds_write2_b32 v13, v76, v77 offset0:164 offset1:230
	v_add_u32_e32 v13, 0x1400, v54
	s_waitcnt vmcnt(12)
	ds_write2_b32 v13, v78, v79 offset0:40 offset1:106
	s_waitcnt vmcnt(10)
	ds_write2_b32 v13, v80, v81 offset0:172 offset1:238
	v_add_u32_e32 v13, 0x1800, v54
	s_waitcnt vmcnt(8)
	ds_write2_b32 v13, v82, v83 offset0:48 offset1:114
	s_waitcnt vmcnt(6)
	ds_write2_b32 v13, v84, v85 offset0:180 offset1:246
	v_add_u32_e32 v13, 0x1c00, v54
	s_waitcnt vmcnt(4)
	ds_write2_b32 v13, v86, v87 offset0:56 offset1:122
	s_waitcnt vmcnt(2)
	ds_write2_b32 v13, v88, v89 offset0:188 offset1:254
	s_waitcnt lgkmcnt(0)
	v_lshl_add_u64 v[12:13], v[8:9], 0, s[2:3]
	s_waitcnt vmcnt(1)
; #define GAS __attribute__((address_space(1)))
; #define LAS __attribute__((address_space(3)))
; #define LDS_WAIT() asm volatile("s_waitcnt lgkmcnt(0)" ::: "memory")
; __device__ __forceinline__ void quant8_item(const float* W, int K, int N, signed char* WT, const gu32* wmax, LAS float* scr, int item, int lane) {
;     ...
;     const int c = lane & 3;
; #pragma unroll
;     for (int j = 0; j < 2; ++j) { const int n = (lane >> 2) + 16 * j; const LAS float* sp = scr + (16 * c) * 33 + n;
;         const float am = __builtin_bit_cast(float, __hip_atomic_load((unsigned*)(wmax + n0 + n), RLX_AGENT));
;         const float inv = 127.0f / fmaxf(am, 1e-30f);
;         unsigned w[4];
; #pragma unroll
;         for (int q = 0; q < 4; ++q) { unsigned pk = 0;
; #pragma unroll
;             for (int i = 0; i < 4; ++i) pk |= ((unsigned)(int)rintf(sp[(4 * q + i) * 33] * inv) & 0xffu) << (8 * i);
;             w[q] = pk; }
;         *(GAS u32x4*)(WT + (size_t)(n0 + n) * K + k0 + 16 * c) = (u32x4){w[0], w[1], w[2], w[3]}; }
;     LDS_WAIT(); asm volatile("" ::: "memory");
	v_max_f32_e32 v2, v90, v90
	v_max_f32_e32 v2, 0xda24260, v2
	v_div_scale_f32 v3, s[2:3], v2, v2, s5
	v_rcp_f32_e32 v4, v3
	s_nop 0
	v_fma_f32 v5, -v3, v4, 1.0
	v_fmac_f32_e32 v4, v5, v4
	v_div_scale_f32 v5, vcc, s5, v2, s5
	v_mul_f32_e32 v16, v5, v4
	v_fma_f32 v17, -v3, v16, v5
	v_fmac_f32_e32 v16, v17, v4
	v_fma_f32 v3, -v3, v16, v5
	v_div_fmas_f32 v3, v3, v4, v16
	v_div_fixup_f32 v18, v3, v2, s5
	ds_read2_b32 v[2:3], v53 offset1:33
	s_waitcnt lgkmcnt(0)
	v_mul_f32_e32 v2, v2, v18
	v_rndne_f32_e32 v2, v2
	v_cvt_i32_f32_e32 v4, v2
	v_mul_f32_e32 v2, v3, v18
	v_rndne_f32_e32 v2, v2
	v_cvt_i32_f32_e32 v2, v2
	v_lshlrev_b32_e32 v5, 8, v2
	ds_read2_b32 v[2:3], v53 offset0:66 offset1:99
	v_perm_b32 v4, v5, v4, s16
	s_waitcnt lgkmcnt(0)
	v_mul_f32_e32 v2, v18, v2
	v_rndne_f32_e32 v2, v2
	v_mul_f32_e32 v3, v18, v3
	v_cvt_i32_f32_sdwa v2, v2 dst_sel:WORD_1 dst_unused:UNUSED_PAD src0_sel:DWORD
	v_rndne_f32_e32 v3, v3
	v_cvt_i32_f32_sdwa v3, v3 dst_sel:BYTE_3 dst_unused:UNUSED_PAD src0_sel:DWORD
	v_and_b32_e32 v2, 0xff0000, v2
	v_or3_b32 v2, v4, v2, v3
	ds_read2_b32 v[4:5], v53 offset0:132 offset1:165
	s_waitcnt lgkmcnt(0)
	v_mul_f32_e32 v3, v18, v4
	v_mul_f32_e32 v4, v18, v5
	v_rndne_f32_e32 v4, v4
	v_rndne_f32_e32 v3, v3
	v_cvt_i32_f32_e32 v4, v4
	v_cvt_i32_f32_e32 v3, v3
	v_lshlrev_b32_e32 v4, 8, v4
	v_perm_b32 v3, v4, v3, s16
	ds_read2_b32 v[4:5], v53 offset0:198 offset1:231
	s_waitcnt lgkmcnt(0)
	v_mul_f32_e32 v4, v18, v4
	v_rndne_f32_e32 v4, v4
	v_mul_f32_e32 v5, v18, v5
	v_cvt_i32_f32_sdwa v4, v4 dst_sel:WORD_1 dst_unused:UNUSED_PAD src0_sel:DWORD
	v_rndne_f32_e32 v5, v5
	v_cvt_i32_f32_sdwa v5, v5 dst_sel:BYTE_3 dst_unused:UNUSED_PAD src0_sel:DWORD
	v_and_b32_e32 v4, 0xff0000, v4
	v_or3_b32 v3, v3, v4, v5
	ds_read2_b32 v[4:5], v55 offset0:8 offset1:41
	s_waitcnt lgkmcnt(0)
	v_mul_f32_e32 v5, v18, v5
	v_mul_f32_e32 v4, v18, v4
	v_rndne_f32_e32 v5, v5
	v_rndne_f32_e32 v4, v4
	v_cvt_i32_f32_e32 v5, v5
	v_cvt_i32_f32_e32 v4, v4
	v_lshlrev_b32_e32 v5, 8, v5
	v_perm_b32 v16, v5, v4, s16
	ds_read2_b32 v[4:5], v55 offset0:74 offset1:107
	s_waitcnt lgkmcnt(0)
	v_mul_f32_e32 v4, v18, v4
	v_rndne_f32_e32 v4, v4
	v_mul_f32_e32 v5, v18, v5
	v_cvt_i32_f32_sdwa v4, v4 dst_sel:WORD_1 dst_unused:UNUSED_PAD src0_sel:DWORD
	v_rndne_f32_e32 v5, v5
	v_cvt_i32_f32_sdwa v5, v5 dst_sel:BYTE_3 dst_unused:UNUSED_PAD src0_sel:DWORD
	v_and_b32_e32 v4, 0xff0000, v4
	v_or3_b32 v4, v16, v4, v5
	ds_read2_b32 v[16:17], v55 offset0:140 offset1:173
	s_waitcnt lgkmcnt(0)
	v_mul_f32_e32 v5, v18, v16
	v_mul_f32_e32 v16, v18, v17
	v_rndne_f32_e32 v16, v16
	v_rndne_f32_e32 v5, v5
	v_cvt_i32_f32_e32 v16, v16
	v_cvt_i32_f32_e32 v5, v5
	v_lshlrev_b32_e32 v16, 8, v16
	v_perm_b32 v5, v16, v5, s16
	ds_read2_b32 v[16:17], v55 offset0:206 offset1:239
	s_waitcnt lgkmcnt(0)
	v_mul_f32_e32 v16, v18, v16
	v_rndne_f32_e32 v16, v16
	v_mul_f32_e32 v17, v18, v17
	v_cvt_i32_f32_sdwa v16, v16 dst_sel:WORD_1 dst_unused:UNUSED_PAD src0_sel:DWORD
	v_rndne_f32_e32 v17, v17
	v_cvt_i32_f32_sdwa v17, v17 dst_sel:BYTE_3 dst_unused:UNUSED_PAD src0_sel:DWORD
	v_and_b32_e32 v16, 0xff0000, v16
	v_or3_b32 v5, v5, v16, v17
	v_add_u32_e32 v16, s0, v52
	v_ashrrev_i32_e32 v17, 31, v16
	v_lshlrev_b64 v[18:19], 10, v[16:17]
	v_lshl_add_u64 v[18:19], v[12:13], 0, v[18:19]
	global_store_dwordx4 v[18:19], v[2:5], off
	s_nop 1
	s_waitcnt vmcnt(1)
	v_max_f32_e32 v2, v91, v91
	v_max_f32_e32 v2, 0xda24260, v2
	v_div_scale_f32 v3, s[0:1], v2, v2, s5
	v_rcp_f32_e32 v4, v3
	s_nop 0
	v_fma_f32 v5, -v3, v4, 1.0
	v_fmac_f32_e32 v4, v5, v4
	v_div_scale_f32 v5, vcc, s5, v2, s5
	v_mul_f32_e32 v14, v5, v4
	v_fma_f32 v15, -v3, v14, v5
	v_fmac_f32_e32 v14, v15, v4
	v_fma_f32 v3, -v3, v14, v5
	v_div_fmas_f32 v3, v3, v4, v14
	v_div_fixup_f32 v17, v3, v2, s5
	ds_read2_b32 v[2:3], v53 offset0:16 offset1:49
	s_waitcnt lgkmcnt(0)
	v_mul_f32_e32 v2, v2, v17
	v_rndne_f32_e32 v2, v2
	v_cvt_i32_f32_e32 v4, v2
	v_mul_f32_e32 v2, v3, v17
	v_rndne_f32_e32 v2, v2
	v_cvt_i32_f32_e32 v2, v2
	v_lshlrev_b32_e32 v5, 8, v2
	ds_read2_b32 v[2:3], v53 offset0:82 offset1:115
	v_perm_b32 v4, v5, v4, s16
	s_waitcnt lgkmcnt(0)
	v_mul_f32_e32 v2, v17, v2
	v_rndne_f32_e32 v2, v2
	v_mul_f32_e32 v3, v17, v3
	v_cvt_i32_f32_sdwa v2, v2 dst_sel:WORD_1 dst_unused:UNUSED_PAD src0_sel:DWORD
	v_rndne_f32_e32 v3, v3
	v_cvt_i32_f32_sdwa v3, v3 dst_sel:BYTE_3 dst_unused:UNUSED_PAD src0_sel:DWORD
	v_and_b32_e32 v2, 0xff0000, v2
	v_or3_b32 v2, v4, v2, v3
	ds_read2_b32 v[4:5], v53 offset0:148 offset1:181
	s_waitcnt lgkmcnt(0)
	v_mul_f32_e32 v3, v17, v4
	v_mul_f32_e32 v4, v17, v5
	v_rndne_f32_e32 v4, v4
	v_rndne_f32_e32 v3, v3
	v_cvt_i32_f32_e32 v4, v4
	v_cvt_i32_f32_e32 v3, v3
	v_lshlrev_b32_e32 v4, 8, v4
	v_perm_b32 v3, v4, v3, s16
	ds_read2_b32 v[4:5], v53 offset0:214 offset1:247
	s_waitcnt lgkmcnt(0)
	v_mul_f32_e32 v4, v17, v4
	v_rndne_f32_e32 v4, v4
	v_mul_f32_e32 v5, v17, v5
	v_cvt_i32_f32_sdwa v4, v4 dst_sel:WORD_1 dst_unused:UNUSED_PAD src0_sel:DWORD
	v_rndne_f32_e32 v5, v5
	v_cvt_i32_f32_sdwa v5, v5 dst_sel:BYTE_3 dst_unused:UNUSED_PAD src0_sel:DWORD
	v_and_b32_e32 v4, 0xff0000, v4
	v_or3_b32 v3, v3, v4, v5
	ds_read2_b32 v[4:5], v55 offset0:24 offset1:57
	s_waitcnt lgkmcnt(0)
	v_mul_f32_e32 v5, v17, v5
	v_mul_f32_e32 v4, v17, v4
	v_rndne_f32_e32 v5, v5
	v_rndne_f32_e32 v4, v4
	v_cvt_i32_f32_e32 v5, v5
	v_cvt_i32_f32_e32 v4, v4
	v_lshlrev_b32_e32 v5, 8, v5
	v_perm_b32 v14, v5, v4, s16
	ds_read2_b32 v[4:5], v55 offset0:90 offset1:123
	s_waitcnt lgkmcnt(0)
	v_mul_f32_e32 v4, v17, v4
	v_rndne_f32_e32 v4, v4
	v_mul_f32_e32 v5, v17, v5
	v_cvt_i32_f32_sdwa v4, v4 dst_sel:WORD_1 dst_unused:UNUSED_PAD src0_sel:DWORD
	v_rndne_f32_e32 v5, v5
	v_cvt_i32_f32_sdwa v5, v5 dst_sel:BYTE_3 dst_unused:UNUSED_PAD src0_sel:DWORD
	v_and_b32_e32 v4, 0xff0000, v4
	v_or3_b32 v4, v14, v4, v5
	ds_read2_b32 v[14:15], v55 offset0:156 offset1:189
	s_waitcnt lgkmcnt(0)
	v_mul_f32_e32 v5, v17, v14
	v_mul_f32_e32 v14, v17, v15
	v_rndne_f32_e32 v14, v14
	v_rndne_f32_e32 v5, v5
	v_cvt_i32_f32_e32 v14, v14
	v_cvt_i32_f32_e32 v5, v5
	v_lshlrev_b32_e32 v14, 8, v14
	v_perm_b32 v5, v14, v5, s16
	ds_read2_b32 v[14:15], v55 offset0:222 offset1:255
	s_waitcnt lgkmcnt(0)
	v_mul_f32_e32 v14, v17, v14
	v_rndne_f32_e32 v14, v14
	v_mul_f32_e32 v15, v17, v15
	v_cvt_i32_f32_sdwa v14, v14 dst_sel:WORD_1 dst_unused:UNUSED_PAD src0_sel:DWORD
	v_rndne_f32_e32 v15, v15
	v_cvt_i32_f32_sdwa v15, v15 dst_sel:BYTE_3 dst_unused:UNUSED_PAD src0_sel:DWORD
	v_and_b32_e32 v14, 0xff0000, v14
	v_or3_b32 v5, v5, v14, v15
	v_add_u32_e32 v14, 16, v16
	v_ashrrev_i32_e32 v15, 31, v14
	v_lshlrev_b64 v[14:15], 10, v[14:15]
	v_lshl_add_u64 v[12:13], v[12:13], 0, v[14:15]
	global_store_dwordx4 v[12:13], v[2:5], off
	s_waitcnt lgkmcnt(0)
	s_cbranch_scc1 .LBB0_1354
	s_mov_b64 s[50:51], s[42:43]
	s_mov_b32 s2, s26
	s_mov_b64 s[48:49], s[40:41]
	s_mov_b64 s[46:47], s[38:39]
	s_mov_b64 s[44:45], s[36:37]
	s_branch .LBB0_1357
